# rstd-from-LDS epilogues incl. GLA gate-lowrank path; dead shuffle/loads replaced by s_nop to keep wait-state distances
# baseline (speedup 1.0000x reference)
; __device__ __forceinline__ void row_rstd8(const float* ssp, int row0, int fq, float (&rs)[2][4]) {
; #pragma unroll
;     for (int ai = 0; ai < 2; ++ai) {
;         f32x4 a[4], b[4];
; #pragma unroll
;         for (int m = 0; m < 4; ++m) { const float* q = ssp + (size_t)(row0 + ai * HALF + m * 16) * 32 + fq * 8; a[m] = *(const f32x4*)q; b[m] = *(const f32x4*)(q + 4); }
; #pragma unroll
;         for (int m = 0; m < 4; ++m) {
;             float s = ((a[m][0] + a[m][1]) + (a[m][2] + a[m][3])) + ((b[m][0] + b[m][1]) + (b[m][2] + b[m][3]));
;             s += __shfl_xor(s, 16); s += __shfl_xor(s, 32);
;             rs[ai][m] = rsqrtf(s * (1.0f / D) + 1e-6f);
;         }
;     }
; }
;     template <int ACT> __device__ __forceinline__ void gated(const f32x4 (&acc)[2][2][4][2], bf16_t* base, int ld, int colbase, int row0, int cl) const {
;         const int fq = (cl >> 3) & 3;
;         const float* ssin = (const float*)(ws + OFF_SUMSQ) + (size_t)ssi * SS_SLOT;
;         float rsv[2][4];
;         row_rstd8(ssin, row0, fq, rsv);
; #pragma unroll
;         for (int ai = 0; ai < 2; ++ai)
; #pragma unroll
;             for (int m = 0; m < 4; ++m) {
;                 const int row = row0 + ai * HALF + m * 16;
;                 const float rs = rsv[ai][m];
.LBB0_577:
	s_and_b64 vcc, exec, s[44:45]
	s_cbranch_vccz .LBB0_579
	v_cmp_lt_i32_e32 vcc, v232, v231
	v_ashrrev_i32_e32 v163, 31, v162
	v_or_b32_e32 v202, 16, v162
	v_cndmask_b32_e32 v130, v229, v232, vcc
	v_cmp_lt_i32_e32 vcc, v230, v231
	v_lshlrev_b32_e32 v205, 2, v130
	v_ashrrev_i32_e32 v203, 31, v202
	v_cndmask_b32_e32 v130, v229, v230, vcc
	v_lshlrev_b32_e32 v177, 2, v130
	s_waitcnt lgkmcnt(0)
	v_lshlrev_b64 v[130:131], 7, v[162:163]
	v_lshl_add_u64 v[134:135], v[190:191], 0, v[130:131]
	s_nop 0
	s_nop 0
	s_nop 0
	v_lshlrev_b64 v[138:139], 7, v[202:203]
	v_lshl_add_u64 v[142:143], v[190:191], 0, v[138:139]
	s_nop 0
	s_nop 0
	s_nop 0
	v_or_b32_e32 v172, 32, v162
	v_ashrrev_i32_e32 v173, 31, v172
	v_lshlrev_b64 v[146:147], 7, v[172:173]
	v_or_b32_e32 v168, 48, v162
	v_lshl_add_u64 v[150:151], v[190:191], 0, v[146:147]
	v_ashrrev_i32_e32 v169, 31, v168
	s_nop 0
	s_nop 0
	s_nop 0
	v_lshlrev_b64 v[154:155], 7, v[168:169]
	v_lshl_add_u64 v[158:159], v[190:191], 0, v[154:155]
	s_nop 0
	s_nop 0
	s_nop 0
	s_mov_b32 s30, 0x358637bd
	v_mov_b64_e32 v[208:209], s[30:31]
	v_add_u32_e32 v174, 0x80, v162
	v_ashrrev_i32_e32 v175, 31, v174
	v_add_u32_e32 v170, 0x90, v162
	v_ashrrev_i32_e32 v171, 31, v170
	v_add_u32_e32 v166, 0xa0, v162
	v_ashrrev_i32_e32 v167, 31, v166
	s_lshl_b32 s58, s82, 7
	s_ashr_i32 s59, s58, 31
	s_nop 0
	v_mov_b32_e32 v164, v130
	v_mov_b32_e32 v165, v134
	v_mov_b32_e32 v134, v131
	v_pk_add_f32 v[130:131], v[164:165], v[134:135]
	v_mov_b32_e32 v134, v132
	v_mov_b32_e32 v135, v136
	v_mov_b32_e32 v136, v133
	v_pk_add_f32 v[132:133], v[134:135], v[136:137]
	v_mov_b32_e32 v134, v140
	v_pk_add_f32 v[130:131], v[130:131], v[132:133]
	v_mov_b32_e32 v132, v138
	v_mov_b32_e32 v133, v142
	v_mov_b32_e32 v142, v139
	v_mov_b32_e32 v135, v144
	v_mov_b32_e32 v144, v141
	v_pk_add_f32 v[132:133], v[132:133], v[142:143]
	v_pk_add_f32 v[134:135], v[134:135], v[144:145]
	v_add_u32_e32 v164, 0xb0, v162
	v_pk_add_f32 v[132:133], v[132:133], v[134:135]
	v_mov_b32_e32 v135, v130
	v_mov_b32_e32 v134, v132
	v_mov_b32_e32 v130, v133
	v_pk_add_f32 v[130:131], v[134:135], v[130:131]
	s_nop 0
	s_nop 0
	v_mov_b32_e32 v134, v156
	v_mov_b32_e32 v135, v160
	v_mov_b32_e32 v160, v157
	v_pk_add_f32 v[134:135], v[134:135], v[160:161]
	s_waitcnt lgkmcnt(0)
	v_pk_add_f32 v[130:131], v[130:131], v[132:133]
	s_nop 0
	s_nop 0
	v_ashrrev_i32_e32 v165, 31, v164
	s_waitcnt lgkmcnt(0)
	v_pk_add_f32 v[130:131], v[130:131], v[132:133]
	s_nop 0
	v_pk_fma_f32 v[130:131], v[130:131], s[22:23], v[208:209] op_sel_hi:[1,0,0]
	v_mov_b32_e32 v133, v152
	v_mul_f32_e32 v132, 0x4b800000, v131
	v_cmp_gt_f32_e64 s[44:45], s23, v131
	v_cmp_gt_f32_e32 vcc, s23, v130
	v_mov_b32_e32 v152, v149
	v_cndmask_b32_e64 v131, v131, v132, s[44:45]
	v_rsq_f32_e32 v131, v131
	s_nop 0
	v_mul_f32_e32 v132, 0x45800000, v131
	v_cndmask_b32_e64 v206, v131, v132, s[44:45]
	ds_read_b32 v206, v242 offset:0
	v_mul_f32_e32 v131, 0x4b800000, v130
	v_cndmask_b32_e32 v130, v130, v131, vcc
	v_rsq_f32_e32 v130, v130
	v_mov_b32_e32 v132, v148
	v_pk_add_f32 v[132:133], v[132:133], v[152:153]
	v_mul_f32_e32 v131, 0x45800000, v130
	v_cndmask_b32_e32 v204, v130, v131, vcc
	ds_read_b32 v204, v242 offset:64
	v_mov_b32_e32 v130, v146
	v_mov_b32_e32 v131, v150
	v_mov_b32_e32 v150, v147
	v_pk_add_f32 v[130:131], v[130:131], v[150:151]
	s_nop 0
	v_pk_add_f32 v[130:131], v[130:131], v[132:133]
	v_mov_b32_e32 v132, v154
	v_mov_b32_e32 v133, v158
	v_mov_b32_e32 v158, v155
	v_pk_add_f32 v[132:133], v[132:133], v[158:159]
	v_lshlrev_b64 v[154:155], 7, v[164:165]
	v_pk_add_f32 v[132:133], v[132:133], v[134:135]
	v_mov_b32_e32 v135, v130
	v_mov_b32_e32 v134, v132
	v_mov_b32_e32 v130, v133
	v_pk_add_f32 v[130:131], v[134:135], v[130:131]
	s_nop 0
	s_nop 0
	v_lshl_add_u64 v[154:155], v[190:191], 0, v[154:155]
	s_waitcnt lgkmcnt(0)
	v_pk_add_f32 v[130:131], v[130:131], v[132:133]
	s_nop 0
	s_nop 0
	s_waitcnt lgkmcnt(0)
	v_pk_add_f32 v[130:131], v[130:131], v[132:133]
	s_nop 0
	v_pk_fma_f32 v[130:131], v[130:131], s[22:23], v[208:209] op_sel_hi:[1,0,0]
	s_nop 0
	v_mul_f32_e32 v132, 0x4b800000, v131
	v_cmp_gt_f32_e64 s[44:45], s23, v131
	v_cmp_gt_f32_e32 vcc, s23, v130
	s_nop 0
	v_cndmask_b32_e64 v131, v131, v132, s[44:45]
	v_rsq_f32_e32 v131, v131
	s_nop 0
	v_mul_f32_e32 v132, 0x45800000, v131
	v_cndmask_b32_e64 v178, v131, v132, s[44:45]
	ds_read_b32 v178, v242 offset:128
	v_mul_f32_e32 v131, 0x4b800000, v130
	v_cndmask_b32_e32 v130, v130, v131, vcc
	v_rsq_f32_e32 v130, v130
	s_nop 0
	v_mul_f32_e32 v131, 0x45800000, v130
	v_cndmask_b32_e32 v176, v130, v131, vcc
	ds_read_b32 v176, v242 offset:192
	v_lshlrev_b64 v[130:131], 7, v[174:175]
	v_lshl_add_u64 v[130:131], v[190:191], 0, v[130:131]
	s_nop 0
	s_nop 0
	v_lshlrev_b64 v[130:131], 7, v[170:171]
	v_lshl_add_u64 v[130:131], v[190:191], 0, v[130:131]
	s_nop 0
	s_nop 0
	v_lshlrev_b64 v[130:131], 7, v[166:167]
	v_lshl_add_u64 v[130:131], v[190:191], 0, v[130:131]
	s_nop 0
	s_nop 0
	s_nop 0
	s_nop 0
	s_nop 0
	s_nop 0
	s_nop 0
	s_nop 0
	v_mov_b32_e32 v210, v142
	s_nop 0
	v_mov_b32_e32 v211, v138
	v_mov_b32_e32 v138, v143
	v_mov_b32_e32 v142, v144
	v_mov_b32_e32 v143, v140
	v_mov_b32_e32 v140, v145
	v_pk_add_f32 v[138:139], v[210:211], v[138:139]
	v_pk_add_f32 v[140:141], v[142:143], v[140:141]
	s_nop 0
	v_mov_b32_e32 v142, v152
	v_pk_add_f32 v[138:139], v[138:139], v[140:141]
	v_mov_b32_e32 v140, v150
	s_nop 0
	v_mov_b32_e32 v141, v146
	v_mov_b32_e32 v146, v151
	v_mov_b32_e32 v143, v148
	v_mov_b32_e32 v148, v153
	v_pk_add_f32 v[140:141], v[140:141], v[146:147]
	v_pk_add_f32 v[142:143], v[142:143], v[148:149]
	s_waitcnt lgkmcnt(0)
; __device__ __forceinline__ float silu_f(float x) { return x * __builtin_amdgcn_rcpf(1.0f + __expf(-x)); }
;     template <int ACT> __device__ __forceinline__ void gated(const f32x4 (&acc)[2][2][4][2], bf16_t* base, int ld, int colbase, int row0, int cl) const {
;         const int fq = (cl >> 3) & 3;
;         const float* ssin = (const float*)(ws + OFF_SUMSQ) + (size_t)ssi * SS_SLOT;
;         float rsv[2][4];
;         row_rstd8(ssin, row0, fq, rsv);
; #pragma unroll
;         for (int ai = 0; ai < 2; ++ai)
; #pragma unroll
;             for (int m = 0; m < 4; ++m) {
;                 const int row = row0 + ai * HALF + m * 16;
;                 const float rs = rsv[ai][m];
;                 float o[8];
; #pragma unroll
;                 for (int n = 0; n < 2; ++n)
; #pragma unroll
;                     for (int j = 0; j < 4; ++j) {
;                         const float g = acc[ai][0][m][n][j] * rs, u = acc[ai][1][m][n][j] * rs;
;                         o[n * 4 + j] = (ACT ? silu_f(g) : g) * u;
;                     }
;                 *(u32x4*)(base + (size_t)row * ld + colbase + cl) = pack8(o);
;             }
	v_pk_mul_f32 v[144:145], v[114:115], v[206:207] op_sel_hi:[1,0]
	v_pk_add_f32 v[140:141], v[140:141], v[142:143]
	v_mov_b32_e32 v143, v138
	v_mov_b32_e32 v142, v140
	v_mov_b32_e32 v138, v141
	v_pk_add_f32 v[138:139], v[142:143], v[138:139]
	s_nop 0
	v_mov_b32_e32 v142, v134
	s_nop 0
	v_mov_b32_e32 v143, v130
	v_mov_b32_e32 v130, v135
	v_mov_b32_e32 v134, v136
	v_mov_b32_e32 v135, v132
	v_mov_b32_e32 v132, v137
	v_pk_add_f32 v[130:131], v[142:143], v[130:131]
	v_pk_add_f32 v[132:133], v[134:135], v[132:133]
	s_nop 0
	v_mov_b32_e32 v134, v160
	v_pk_add_f32 v[130:131], v[130:131], v[132:133]
	v_mov_b32_e32 v132, v158
	s_nop 0
	v_mov_b32_e32 v133, v154
	v_mov_b32_e32 v154, v159
	v_mov_b32_e32 v135, v156
	v_mov_b32_e32 v156, v161
	v_pk_add_f32 v[132:133], v[132:133], v[154:155]
	v_pk_add_f32 v[134:135], v[134:135], v[156:157]
	v_pk_mul_f32 v[136:137], v[126:127], v[206:207] op_sel_hi:[1,0]
	v_pk_add_f32 v[132:133], v[132:133], v[134:135]
	v_mov_b32_e32 v135, v130
	v_mov_b32_e32 v134, v132
	v_mov_b32_e32 v130, v133
	v_pk_add_f32 v[130:131], v[134:135], v[130:131]
	s_nop 0
	s_nop 0
	v_pk_mul_f32 v[146:147], v[116:117], v[206:207] op_sel_hi:[1,0]
	s_nop 0
	s_nop 0
	v_pk_mul_f32 v[148:149], v[106:107], v[206:207] op_sel_hi:[1,0]
	s_waitcnt lgkmcnt(2)
	v_pk_add_f32 v[130:131], v[130:131], v[132:133]
	s_nop 0
	s_nop 0
	s_waitcnt lgkmcnt(2)
	v_pk_add_f32 v[138:139], v[138:139], v[140:141]
	s_nop 0
	s_nop 0
	v_pk_mul_f32 v[150:151], v[108:109], v[206:207] op_sel_hi:[1,0]
	s_waitcnt lgkmcnt(2)
	v_pk_add_f32 v[130:131], v[130:131], v[132:133]
	v_mul_f32_e32 v133, 0xbfb8aa3b, v136
	v_exp_f32_e32 v133, v133
	s_waitcnt lgkmcnt(0)
	v_pk_add_f32 v[138:139], v[138:139], v[140:141]
	v_pk_fma_f32 v[130:131], v[130:131], s[22:23], v[208:209] op_sel_hi:[1,0,0]
	v_pk_fma_f32 v[138:139], v[138:139], s[22:23], v[208:209] op_sel_hi:[1,0,0]
	v_add_f32_e32 v133, 1.0, v133
	v_rcp_f32_e32 v142, v133
	v_mul_f32_e32 v133, 0xbfb8aa3b, v137
	v_exp_f32_e32 v133, v133
	v_mul_f32_e32 v140, 0x4b800000, v139
	v_cmp_gt_f32_e64 s[44:45], s23, v139
	v_cmp_gt_f32_e32 vcc, s23, v138
	v_add_f32_e32 v133, 1.0, v133
	v_rcp_f32_e32 v143, v133
	v_cndmask_b32_e64 v139, v139, v140, s[44:45]
	v_rsq_f32_e32 v139, v139
	v_mul_f32_e32 v132, 0x4b800000, v131
	v_pk_mul_f32 v[136:137], v[136:137], v[142:143]
	v_pk_mul_f32 v[142:143], v[128:129], v[206:207] op_sel_hi:[1,0]
	v_pk_mul_f32 v[136:137], v[144:145], v[136:137]
	v_mul_f32_e32 v133, 0xbfb8aa3b, v142
	v_exp_f32_e32 v133, v133
	v_mul_f32_e32 v140, 0x45800000, v139
	v_cndmask_b32_e64 v140, v139, v140, s[44:45]
	ds_read_b32 v140, v242 offset:512
	v_mul_f32_e32 v139, 0x4b800000, v138
	v_add_f32_e32 v133, 1.0, v133
	v_rcp_f32_e32 v144, v133
	v_mul_f32_e32 v133, 0xbfb8aa3b, v143
	v_exp_f32_e32 v133, v133
	v_cmp_gt_f32_e64 s[44:45], s23, v131
	v_cndmask_b32_e32 v138, v138, v139, vcc
	v_rsq_f32_e32 v138, v138
	v_add_f32_e32 v133, 1.0, v133
	v_rcp_f32_e32 v145, v133
	v_cndmask_b32_e64 v131, v131, v132, s[44:45]
	v_rsq_f32_e32 v131, v131
	v_mul_f32_e32 v139, 0x45800000, v138
	v_pk_mul_f32 v[142:143], v[142:143], v[144:145]
	v_cndmask_b32_e32 v138, v138, v139, vcc
	ds_read_b32 v138, v242 offset:576
	v_pk_mul_f32 v[144:145], v[146:147], v[142:143]
	v_pk_mul_f32 v[142:143], v[122:123], v[206:207] op_sel_hi:[1,0]
	v_mul_f32_e32 v132, 0x45800000, v131
	v_mul_f32_e32 v133, 0xbfb8aa3b, v142
	v_exp_f32_e32 v133, v133
	v_cmp_gt_f32_e32 vcc, s23, v130
	v_cndmask_b32_e64 v134, v131, v132, s[44:45]
	ds_read_b32 v134, v242 offset:640
	v_mul_f32_e32 v131, 0x4b800000, v130
	v_add_f32_e32 v133, 1.0, v133
	v_rcp_f32_e32 v146, v133
	v_mul_f32_e32 v133, 0xbfb8aa3b, v143
	v_exp_f32_e32 v133, v133
	v_cndmask_b32_e32 v130, v130, v131, vcc
	v_rsq_f32_e32 v130, v130
	v_add_f32_e32 v133, 1.0, v133
	v_rcp_f32_e32 v147, v133
	v_mul_f32_e32 v131, 0x45800000, v130
	v_cndmask_b32_e32 v132, v130, v131, vcc
	ds_read_b32 v132, v242 offset:704
	v_lshl_add_u64 v[130:131], s[58:59], 1, v[188:189]
	v_pk_mul_f32 v[142:143], v[142:143], v[146:147]
	s_movk_i32 s58, 0x2c00
	v_pk_mul_f32 v[146:147], v[148:149], v[142:143]
	v_pk_mul_f32 v[142:143], v[124:125], v[206:207] op_sel_hi:[1,0]
	s_nop 0
	v_mul_f32_e32 v133, 0xbfb8aa3b, v142
	v_exp_f32_e32 v133, v133
	s_nop 0
	v_add_f32_e32 v133, 1.0, v133
	v_rcp_f32_e32 v148, v133
	v_mul_f32_e32 v133, 0xbfb8aa3b, v143
	v_exp_f32_e32 v133, v133
	s_nop 0
	v_add_f32_e32 v133, 1.0, v133
	v_rcp_f32_e32 v149, v133
	s_nop 0
	v_pk_mul_f32 v[142:143], v[142:143], v[148:149]
	s_nop 0
	v_pk_mul_f32 v[148:149], v[150:151], v[142:143]
	v_cvt_pk_bf16_f32 v142, v136, v137
	v_cvt_pk_bf16_f32 v143, v144, v145
	v_cvt_pk_bf16_f32 v144, v146, v147
	v_cvt_pk_bf16_f32 v145, v148, v149
	v_mad_i64_i32 v[136:137], s[44:45], v162, s58, v[130:131]
	global_store_dwordx4 v[136:137], v[142:145], off
	s_waitcnt lgkmcnt(0)
; __device__ __forceinline__ float silu_f(float x) { return x * __builtin_amdgcn_rcpf(1.0f + __expf(-x)); }
;     template <int ACT> __device__ __forceinline__ void gated(const f32x4 (&acc)[2][2][4][2], bf16_t* base, int ld, int colbase, int row0, int cl) const {
;     ...
;                 float o[8];
; #pragma unroll
;                 for (int n = 0; n < 2; ++n)
; #pragma unroll
;                     for (int j = 0; j < 4; ++j) {
;                         const float g = acc[ai][0][m][n][j] * rs, u = acc[ai][1][m][n][j] * rs;
;                         o[n * 4 + j] = (ACT ? silu_f(g) : g) * u;
;                     }
;                 *(u32x4*)(base + (size_t)row * ld + colbase + cl) = pack8(o);
;             }
	v_pk_mul_f32 v[136:137], v[118:119], v[204:205] op_sel_hi:[1,0]
	v_pk_mul_f32 v[146:147], v[100:101], v[204:205] op_sel_hi:[1,0]
	v_mul_f32_e32 v133, 0xbfb8aa3b, v136
	v_exp_f32_e32 v133, v133
	v_pk_mul_f32 v[144:145], v[98:99], v[204:205] op_sel_hi:[1,0]
	v_pk_mul_f32 v[148:149], v[90:91], v[204:205] op_sel_hi:[1,0]
	v_pk_mul_f32 v[150:151], v[92:93], v[204:205] op_sel_hi:[1,0]
	v_add_f32_e32 v133, 1.0, v133
	v_rcp_f32_e32 v142, v133
	v_mul_f32_e32 v133, 0xbfb8aa3b, v137
	v_exp_f32_e32 v133, v133
	s_nop 0
	v_add_f32_e32 v133, 1.0, v133
	v_rcp_f32_e32 v143, v133
	s_nop 0
	v_pk_mul_f32 v[136:137], v[136:137], v[142:143]
	v_pk_mul_f32 v[142:143], v[120:121], v[204:205] op_sel_hi:[1,0]
	v_pk_mul_f32 v[136:137], v[144:145], v[136:137]
	v_mul_f32_e32 v133, 0xbfb8aa3b, v142
	v_exp_f32_e32 v133, v133
	s_nop 0
	v_add_f32_e32 v133, 1.0, v133
	v_rcp_f32_e32 v144, v133
	v_mul_f32_e32 v133, 0xbfb8aa3b, v143
	v_exp_f32_e32 v133, v133
	s_nop 0
	v_add_f32_e32 v133, 1.0, v133
	v_rcp_f32_e32 v145, v133
	s_nop 0
	v_pk_mul_f32 v[142:143], v[142:143], v[144:145]
	s_nop 0
	v_pk_mul_f32 v[144:145], v[146:147], v[142:143]
	v_pk_mul_f32 v[142:143], v[110:111], v[204:205] op_sel_hi:[1,0]
	s_nop 0
	v_mul_f32_e32 v133, 0xbfb8aa3b, v142
	v_exp_f32_e32 v133, v133
	s_nop 0
	v_add_f32_e32 v133, 1.0, v133
	v_rcp_f32_e32 v146, v133
	v_mul_f32_e32 v133, 0xbfb8aa3b, v143
	v_exp_f32_e32 v133, v133
	s_nop 0
	v_add_f32_e32 v133, 1.0, v133
	v_rcp_f32_e32 v147, v133
	s_nop 0
	v_pk_mul_f32 v[142:143], v[142:143], v[146:147]
	s_nop 0
	v_pk_mul_f32 v[146:147], v[148:149], v[142:143]
	v_pk_mul_f32 v[142:143], v[112:113], v[204:205] op_sel_hi:[1,0]
	s_nop 0
	v_mul_f32_e32 v133, 0xbfb8aa3b, v142
	v_exp_f32_e32 v133, v133
	s_nop 0
	v_add_f32_e32 v133, 1.0, v133
	v_rcp_f32_e32 v148, v133
	v_mul_f32_e32 v133, 0xbfb8aa3b, v143
	v_exp_f32_e32 v133, v133
	s_nop 0
	v_add_f32_e32 v133, 1.0, v133
	v_rcp_f32_e32 v149, v133
	s_nop 0
	v_pk_mul_f32 v[142:143], v[142:143], v[148:149]
	s_nop 0
	v_pk_mul_f32 v[148:149], v[150:151], v[142:143]
	v_cvt_pk_bf16_f32 v142, v136, v137
	v_cvt_pk_bf16_f32 v143, v144, v145
	v_cvt_pk_bf16_f32 v144, v146, v147
	v_cvt_pk_bf16_f32 v145, v148, v149
	v_mad_i64_i32 v[136:137], s[44:45], v202, s58, v[130:131]
	global_store_dwordx4 v[136:137], v[142:145], off
	s_waitcnt lgkmcnt(0)
	v_pk_mul_f32 v[136:137], v[102:103], v[178:179] op_sel_hi:[1,0]
	v_pk_mul_f32 v[146:147], v[84:85], v[178:179] op_sel_hi:[1,0]
	v_mul_f32_e32 v133, 0xbfb8aa3b, v136
	v_exp_f32_e32 v133, v133
	v_pk_mul_f32 v[144:145], v[82:83], v[178:179] op_sel_hi:[1,0]
	v_pk_mul_f32 v[148:149], v[74:75], v[178:179] op_sel_hi:[1,0]
	v_pk_mul_f32 v[150:151], v[76:77], v[178:179] op_sel_hi:[1,0]
	v_add_f32_e32 v133, 1.0, v133
	v_rcp_f32_e32 v142, v133
	v_mul_f32_e32 v133, 0xbfb8aa3b, v137
	v_exp_f32_e32 v133, v133
	s_nop 0
	v_add_f32_e32 v133, 1.0, v133
	v_rcp_f32_e32 v143, v133
	s_nop 0
	v_pk_mul_f32 v[136:137], v[136:137], v[142:143]
	v_pk_mul_f32 v[142:143], v[104:105], v[178:179] op_sel_hi:[1,0]
	v_pk_mul_f32 v[136:137], v[144:145], v[136:137]
	v_mul_f32_e32 v133, 0xbfb8aa3b, v142
	v_exp_f32_e32 v133, v133
	s_nop 0
	v_add_f32_e32 v133, 1.0, v133
	v_rcp_f32_e32 v144, v133
	v_mul_f32_e32 v133, 0xbfb8aa3b, v143
	v_exp_f32_e32 v133, v133
	s_nop 0
	v_add_f32_e32 v133, 1.0, v133
	v_rcp_f32_e32 v145, v133
	s_nop 0
	v_pk_mul_f32 v[142:143], v[142:143], v[144:145]
	s_nop 0
	v_pk_mul_f32 v[144:145], v[146:147], v[142:143]
	v_pk_mul_f32 v[142:143], v[94:95], v[178:179] op_sel_hi:[1,0]
	s_nop 0
	v_mul_f32_e32 v133, 0xbfb8aa3b, v142
	v_exp_f32_e32 v133, v133
	s_nop 0
	v_add_f32_e32 v133, 1.0, v133
	v_rcp_f32_e32 v146, v133
	v_mul_f32_e32 v133, 0xbfb8aa3b, v143
	v_exp_f32_e32 v133, v133
	s_nop 0
	v_add_f32_e32 v133, 1.0, v133
	v_rcp_f32_e32 v147, v133
	s_nop 0
	v_pk_mul_f32 v[142:143], v[142:143], v[146:147]
	s_nop 0
	v_pk_mul_f32 v[146:147], v[148:149], v[142:143]
	v_pk_mul_f32 v[142:143], v[96:97], v[178:179] op_sel_hi:[1,0]
	s_nop 0
	v_mul_f32_e32 v133, 0xbfb8aa3b, v142
	v_exp_f32_e32 v133, v133
	s_nop 0
	v_add_f32_e32 v133, 1.0, v133
	v_rcp_f32_e32 v148, v133
	v_mul_f32_e32 v133, 0xbfb8aa3b, v143
	v_exp_f32_e32 v133, v133
	s_nop 0
	v_add_f32_e32 v133, 1.0, v133
	v_rcp_f32_e32 v149, v133
	s_nop 0
	v_pk_mul_f32 v[142:143], v[142:143], v[148:149]
	s_nop 0
	v_pk_mul_f32 v[148:149], v[150:151], v[142:143]
	v_cvt_pk_bf16_f32 v142, v136, v137
	v_cvt_pk_bf16_f32 v143, v144, v145
	v_cvt_pk_bf16_f32 v144, v146, v147
	v_cvt_pk_bf16_f32 v145, v148, v149
	v_mad_i64_i32 v[136:137], s[44:45], v172, s58, v[130:131]
	global_store_dwordx4 v[136:137], v[142:145], off
	s_waitcnt lgkmcnt(0)
; __device__ __forceinline__ float silu_f(float x) { return x * __builtin_amdgcn_rcpf(1.0f + __expf(-x)); }
;     template <int ACT> __device__ __forceinline__ void gated(const f32x4 (&acc)[2][2][4][2], bf16_t* base, int ld, int colbase, int row0, int cl) const {
;     ...
;                 float o[8];
; #pragma unroll
;                 for (int n = 0; n < 2; ++n)
; #pragma unroll
;                     for (int j = 0; j < 4; ++j) {
;                         const float g = acc[ai][0][m][n][j] * rs, u = acc[ai][1][m][n][j] * rs;
;                         o[n * 4 + j] = (ACT ? silu_f(g) : g) * u;
;                     }
;                 *(u32x4*)(base + (size_t)row * ld + colbase + cl) = pack8(o);
;             }
	v_pk_mul_f32 v[136:137], v[86:87], v[176:177] op_sel_hi:[1,0]
	v_pk_mul_f32 v[146:147], v[72:73], v[176:177] op_sel_hi:[1,0]
	v_mul_f32_e32 v133, 0xbfb8aa3b, v136
	v_exp_f32_e32 v133, v133
	v_pk_mul_f32 v[144:145], v[70:71], v[176:177] op_sel_hi:[1,0]
	v_pk_mul_f32 v[148:149], v[66:67], v[176:177] op_sel_hi:[1,0]
	v_pk_mul_f32 v[150:151], v[68:69], v[176:177] op_sel_hi:[1,0]
	v_add_f32_e32 v133, 1.0, v133
	v_rcp_f32_e32 v142, v133
	v_mul_f32_e32 v133, 0xbfb8aa3b, v137
	v_exp_f32_e32 v133, v133
	s_nop 0
	v_add_f32_e32 v133, 1.0, v133
	v_rcp_f32_e32 v143, v133
	s_nop 0
	v_pk_mul_f32 v[136:137], v[136:137], v[142:143]
	v_pk_mul_f32 v[142:143], v[88:89], v[176:177] op_sel_hi:[1,0]
	v_pk_mul_f32 v[136:137], v[144:145], v[136:137]
	v_mul_f32_e32 v133, 0xbfb8aa3b, v142
	v_exp_f32_e32 v133, v133
	s_nop 0
	v_add_f32_e32 v133, 1.0, v133
	v_rcp_f32_e32 v144, v133
	v_mul_f32_e32 v133, 0xbfb8aa3b, v143
	v_exp_f32_e32 v133, v133
	s_nop 0
	v_add_f32_e32 v133, 1.0, v133
	v_rcp_f32_e32 v145, v133
	s_nop 0
	v_pk_mul_f32 v[142:143], v[142:143], v[144:145]
	s_nop 0
	v_pk_mul_f32 v[144:145], v[146:147], v[142:143]
	v_pk_mul_f32 v[142:143], v[78:79], v[176:177] op_sel_hi:[1,0]
	s_nop 0
	v_mul_f32_e32 v133, 0xbfb8aa3b, v142
	v_exp_f32_e32 v133, v133
	s_nop 0
	v_add_f32_e32 v133, 1.0, v133
	v_rcp_f32_e32 v146, v133
	v_mul_f32_e32 v133, 0xbfb8aa3b, v143
	v_exp_f32_e32 v133, v133
	s_nop 0
	v_add_f32_e32 v133, 1.0, v133
	v_rcp_f32_e32 v147, v133
	s_nop 0
	v_pk_mul_f32 v[142:143], v[142:143], v[146:147]
	s_nop 0
	v_pk_mul_f32 v[146:147], v[148:149], v[142:143]
	v_pk_mul_f32 v[142:143], v[80:81], v[176:177] op_sel_hi:[1,0]
	s_nop 0
	v_mul_f32_e32 v133, 0xbfb8aa3b, v142
	v_exp_f32_e32 v133, v133
	s_nop 0
	v_add_f32_e32 v133, 1.0, v133
	v_rcp_f32_e32 v148, v133
	v_mul_f32_e32 v133, 0xbfb8aa3b, v143
	v_exp_f32_e32 v133, v133
	s_nop 0
	v_add_f32_e32 v133, 1.0, v133
	v_rcp_f32_e32 v149, v133
	s_nop 0
	v_pk_mul_f32 v[142:143], v[142:143], v[148:149]
	s_nop 0
	v_pk_mul_f32 v[148:149], v[150:151], v[142:143]
	v_cvt_pk_bf16_f32 v142, v136, v137
	v_cvt_pk_bf16_f32 v143, v144, v145
	v_cvt_pk_bf16_f32 v144, v146, v147
	v_cvt_pk_bf16_f32 v145, v148, v149
	v_mad_i64_i32 v[136:137], s[44:45], v168, s58, v[130:131]
	global_store_dwordx4 v[136:137], v[142:145], off
	s_waitcnt lgkmcnt(0)
	v_pk_mul_f32 v[136:137], v[62:63], v[140:141] op_sel_hi:[1,0]
	v_pk_mul_f32 v[146:147], v[48:49], v[140:141] op_sel_hi:[1,0]
	v_mul_f32_e32 v133, 0xbfb8aa3b, v136
	v_exp_f32_e32 v133, v133
	v_pk_mul_f32 v[144:145], v[46:47], v[140:141] op_sel_hi:[1,0]
	v_pk_mul_f32 v[148:149], v[42:43], v[140:141] op_sel_hi:[1,0]
	v_add_f32_e32 v133, 1.0, v133
	v_rcp_f32_e32 v142, v133
	v_mul_f32_e32 v133, 0xbfb8aa3b, v137
	v_exp_f32_e32 v133, v133
	s_nop 0
	v_add_f32_e32 v133, 1.0, v133
	v_rcp_f32_e32 v143, v133
	s_nop 0
	v_pk_mul_f32 v[136:137], v[136:137], v[142:143]
	v_pk_mul_f32 v[142:143], v[64:65], v[140:141] op_sel_hi:[1,0]
	v_pk_mul_f32 v[136:137], v[144:145], v[136:137]
	v_mul_f32_e32 v133, 0xbfb8aa3b, v142
	v_exp_f32_e32 v133, v133
	s_nop 0
	v_add_f32_e32 v133, 1.0, v133
	v_rcp_f32_e32 v144, v133
	v_mul_f32_e32 v133, 0xbfb8aa3b, v143
	v_exp_f32_e32 v133, v133
	s_nop 0
	v_add_f32_e32 v133, 1.0, v133
	v_rcp_f32_e32 v145, v133
	s_nop 0
	v_pk_mul_f32 v[142:143], v[142:143], v[144:145]
	v_pk_mul_f32 v[144:145], v[58:59], v[140:141] op_sel_hi:[1,0]
	v_pk_mul_f32 v[142:143], v[146:147], v[142:143]
	v_mul_f32_e32 v133, 0xbfb8aa3b, v144
	v_exp_f32_e32 v133, v133
	s_nop 0
	v_add_f32_e32 v133, 1.0, v133
	v_rcp_f32_e32 v146, v133
	v_mul_f32_e32 v133, 0xbfb8aa3b, v145
	v_exp_f32_e32 v133, v133
	s_nop 0
	v_add_f32_e32 v133, 1.0, v133
	v_rcp_f32_e32 v147, v133
	s_nop 0
	v_pk_mul_f32 v[144:145], v[144:145], v[146:147]
	v_pk_mul_f32 v[146:147], v[60:61], v[140:141] op_sel_hi:[1,0]
	v_pk_mul_f32 v[144:145], v[148:149], v[144:145]
	v_mul_f32_e32 v133, 0xbfb8aa3b, v146
	v_exp_f32_e32 v133, v133
	v_pk_mul_f32 v[140:141], v[44:45], v[140:141] op_sel_hi:[1,0]
	v_add_f32_e32 v133, 1.0, v133
	v_rcp_f32_e32 v148, v133
	v_mul_f32_e32 v133, 0xbfb8aa3b, v147
	v_exp_f32_e32 v133, v133
	s_nop 0
	v_add_f32_e32 v133, 1.0, v133
	v_rcp_f32_e32 v149, v133
	s_nop 0
	v_pk_mul_f32 v[146:147], v[146:147], v[148:149]
	s_nop 0
	v_pk_mul_f32 v[146:147], v[140:141], v[146:147]
	v_cvt_pk_bf16_f32 v140, v136, v137
	v_cvt_pk_bf16_f32 v141, v142, v143
	v_cvt_pk_bf16_f32 v142, v144, v145
	v_cvt_pk_bf16_f32 v143, v146, v147
	v_mad_i64_i32 v[136:137], s[44:45], v174, s58, v[130:131]
	global_store_dwordx4 v[136:137], v[140:143], off
	s_waitcnt lgkmcnt(0)
; __device__ __forceinline__ float silu_f(float x) { return x * __builtin_amdgcn_rcpf(1.0f + __expf(-x)); }
;     template <int ACT> __device__ __forceinline__ void gated(const f32x4 (&acc)[2][2][4][2], bf16_t* base, int ld, int colbase, int row0, int cl) const {
;     ...
;                 float o[8];
; #pragma unroll
;                 for (int n = 0; n < 2; ++n)
; #pragma unroll
;                     for (int j = 0; j < 4; ++j) {
;                         const float g = acc[ai][0][m][n][j] * rs, u = acc[ai][1][m][n][j] * rs;
;                         o[n * 4 + j] = (ACT ? silu_f(g) : g) * u;
;                     }
;                 *(u32x4*)(base + (size_t)row * ld + colbase + cl) = pack8(o);
;             }
	v_pk_mul_f32 v[136:137], v[54:55], v[138:139] op_sel_hi:[1,0]
	v_pk_mul_f32 v[144:145], v[32:33], v[138:139] op_sel_hi:[1,0]
	v_mul_f32_e32 v133, 0xbfb8aa3b, v136
	v_exp_f32_e32 v133, v133
	v_pk_mul_f32 v[142:143], v[30:31], v[138:139] op_sel_hi:[1,0]
	v_pk_mul_f32 v[146:147], v[26:27], v[138:139] op_sel_hi:[1,0]
	v_add_f32_e32 v133, 1.0, v133
	v_rcp_f32_e32 v140, v133
	v_mul_f32_e32 v133, 0xbfb8aa3b, v137
	v_exp_f32_e32 v133, v133
	s_nop 0
	v_add_f32_e32 v133, 1.0, v133
	v_rcp_f32_e32 v141, v133
	s_nop 0
	v_pk_mul_f32 v[136:137], v[136:137], v[140:141]
	v_pk_mul_f32 v[140:141], v[56:57], v[138:139] op_sel_hi:[1,0]
	v_pk_mul_f32 v[136:137], v[142:143], v[136:137]
	v_mul_f32_e32 v133, 0xbfb8aa3b, v140
	v_exp_f32_e32 v133, v133
	v_cvt_pk_bf16_f32 v136, v136, v137
	v_add_f32_e32 v133, 1.0, v133
	v_rcp_f32_e32 v142, v133
	v_mul_f32_e32 v133, 0xbfb8aa3b, v141
	v_exp_f32_e32 v133, v133
	s_nop 0
	v_add_f32_e32 v133, 1.0, v133
	v_rcp_f32_e32 v143, v133
	s_nop 0
	v_pk_mul_f32 v[140:141], v[140:141], v[142:143]
	v_pk_mul_f32 v[142:143], v[50:51], v[138:139] op_sel_hi:[1,0]
	v_pk_mul_f32 v[140:141], v[144:145], v[140:141]
	v_mul_f32_e32 v133, 0xbfb8aa3b, v142
	v_exp_f32_e32 v133, v133
	v_cvt_pk_bf16_f32 v137, v140, v141
	v_mad_i64_i32 v[140:141], s[44:45], v170, s58, v[130:131]
	v_add_f32_e32 v133, 1.0, v133
	v_rcp_f32_e32 v144, v133
	v_mul_f32_e32 v133, 0xbfb8aa3b, v143
	v_exp_f32_e32 v133, v133
	s_nop 0
	v_add_f32_e32 v133, 1.0, v133
	v_rcp_f32_e32 v145, v133
	s_nop 0
	v_pk_mul_f32 v[142:143], v[142:143], v[144:145]
	v_pk_mul_f32 v[144:145], v[52:53], v[138:139] op_sel_hi:[1,0]
	v_pk_mul_f32 v[142:143], v[146:147], v[142:143]
	v_mul_f32_e32 v133, 0xbfb8aa3b, v144
	v_exp_f32_e32 v133, v133
	v_pk_mul_f32 v[138:139], v[28:29], v[138:139] op_sel_hi:[1,0]
	v_add_f32_e32 v133, 1.0, v133
	v_rcp_f32_e32 v146, v133
	v_mul_f32_e32 v133, 0xbfb8aa3b, v145
	v_exp_f32_e32 v133, v133
	s_nop 0
	v_add_f32_e32 v133, 1.0, v133
	v_rcp_f32_e32 v147, v133
	s_nop 0
	v_pk_mul_f32 v[144:145], v[144:145], v[146:147]
	s_nop 0
	v_pk_mul_f32 v[144:145], v[138:139], v[144:145]
	v_cvt_pk_bf16_f32 v138, v142, v143
	v_cvt_pk_bf16_f32 v139, v144, v145
	global_store_dwordx4 v[140:141], v[136:139], off
	s_waitcnt lgkmcnt(0)
	v_pk_mul_f32 v[140:141], v[14:15], v[134:135] op_sel_hi:[1,0]
	v_pk_mul_f32 v[142:143], v[16:17], v[134:135] op_sel_hi:[1,0]
	v_pk_mul_f32 v[136:137], v[38:39], v[134:135] op_sel_hi:[1,0]
	v_pk_mul_f32 v[144:145], v[10:11], v[134:135] op_sel_hi:[1,0]
	v_mul_f32_e32 v133, 0xbfb8aa3b, v136
	v_exp_f32_e32 v133, v133
	s_nop 0
	v_add_f32_e32 v133, 1.0, v133
	v_rcp_f32_e32 v138, v133
	v_mul_f32_e32 v133, 0xbfb8aa3b, v137
	v_exp_f32_e32 v133, v133
	s_nop 0
	v_add_f32_e32 v133, 1.0, v133
	v_rcp_f32_e32 v139, v133
	s_nop 0
	v_pk_mul_f32 v[136:137], v[136:137], v[138:139]
	v_pk_mul_f32 v[138:139], v[40:41], v[134:135] op_sel_hi:[1,0]
	v_pk_mul_f32 v[136:137], v[140:141], v[136:137]
	v_mul_f32_e32 v133, 0xbfb8aa3b, v138
	v_exp_f32_e32 v133, v133
	s_nop 0
	v_add_f32_e32 v133, 1.0, v133
	v_rcp_f32_e32 v140, v133
	v_mul_f32_e32 v133, 0xbfb8aa3b, v139
	v_exp_f32_e32 v133, v133
	s_nop 0
	v_add_f32_e32 v133, 1.0, v133
	v_rcp_f32_e32 v141, v133
	s_nop 0
	v_pk_mul_f32 v[138:139], v[138:139], v[140:141]
	v_pk_mul_f32 v[140:141], v[34:35], v[134:135] op_sel_hi:[1,0]
	v_pk_mul_f32 v[138:139], v[142:143], v[138:139]
	v_mul_f32_e32 v133, 0xbfb8aa3b, v140
	v_exp_f32_e32 v133, v133
	s_nop 0
	v_add_f32_e32 v133, 1.0, v133
	v_rcp_f32_e32 v142, v133
	v_mul_f32_e32 v133, 0xbfb8aa3b, v141
	v_exp_f32_e32 v133, v133
	s_nop 0
	v_add_f32_e32 v133, 1.0, v133
	v_rcp_f32_e32 v143, v133
	s_nop 0
	v_pk_mul_f32 v[140:141], v[140:141], v[142:143]
	v_pk_mul_f32 v[142:143], v[36:37], v[134:135] op_sel_hi:[1,0]
	v_pk_mul_f32 v[140:141], v[144:145], v[140:141]
	v_mul_f32_e32 v133, 0xbfb8aa3b, v142
	v_exp_f32_e32 v133, v133
	v_pk_mul_f32 v[134:135], v[12:13], v[134:135] op_sel_hi:[1,0]
	v_add_f32_e32 v133, 1.0, v133
	v_rcp_f32_e32 v144, v133
	v_mul_f32_e32 v133, 0xbfb8aa3b, v143
	v_exp_f32_e32 v133, v133
	s_nop 0
	v_add_f32_e32 v133, 1.0, v133
	v_rcp_f32_e32 v145, v133
	s_nop 0
	v_pk_mul_f32 v[142:143], v[142:143], v[144:145]
	s_nop 0
	v_pk_mul_f32 v[142:143], v[134:135], v[142:143]
	v_cvt_pk_bf16_f32 v134, v136, v137
	v_cvt_pk_bf16_f32 v135, v138, v139
	v_cvt_pk_bf16_f32 v136, v140, v141
	v_cvt_pk_bf16_f32 v137, v142, v143
	v_mad_i64_i32 v[138:139], s[44:45], v166, s58, v[130:131]
	global_store_dwordx4 v[138:139], v[134:137], off
	v_mad_i64_i32 v[130:131], s[44:45], v164, s58, v[130:131]
	s_nop 0
	s_waitcnt lgkmcnt(0)
	v_pk_mul_f32 v[134:135], v[22:23], v[132:133] op_sel_hi:[1,0]
	s_nop 0
	v_mul_f32_e32 v133, 0xbfb8aa3b, v134
	v_exp_f32_e32 v133, v133
	s_nop 0
	v_add_f32_e32 v133, 1.0, v133
	v_rcp_f32_e32 v136, v133
	v_pk_mul_f32 v[138:139], v[6:7], v[132:133] op_sel_hi:[1,0]
	v_mul_f32_e32 v133, 0xbfb8aa3b, v135
	v_exp_f32_e32 v133, v133
	s_nop 0
	v_add_f32_e32 v133, 1.0, v133
	v_rcp_f32_e32 v137, v133
	s_nop 0
	v_pk_mul_f32 v[134:135], v[134:135], v[136:137]
	v_pk_mul_f32 v[136:137], v[24:25], v[132:133] op_sel_hi:[1,0]
	v_pk_mul_f32 v[134:135], v[138:139], v[134:135]
	v_mul_f32_e32 v133, 0xbfb8aa3b, v136
	v_exp_f32_e32 v133, v133
	s_nop 0
	v_add_f32_e32 v133, 1.0, v133
	v_rcp_f32_e32 v138, v133
	v_pk_mul_f32 v[140:141], v[8:9], v[132:133] op_sel_hi:[1,0]
	v_mul_f32_e32 v133, 0xbfb8aa3b, v137
	v_exp_f32_e32 v133, v133
	s_nop 0
	v_add_f32_e32 v133, 1.0, v133
	v_rcp_f32_e32 v139, v133
	s_nop 0
	v_pk_mul_f32 v[136:137], v[136:137], v[138:139]
	v_pk_mul_f32 v[138:139], v[18:19], v[132:133] op_sel_hi:[1,0]
	v_pk_mul_f32 v[136:137], v[140:141], v[136:137]
	v_mul_f32_e32 v133, 0xbfb8aa3b, v138
	v_exp_f32_e32 v133, v133
	s_nop 0
	v_add_f32_e32 v133, 1.0, v133
	v_rcp_f32_e32 v140, v133
	v_pk_mul_f32 v[142:143], v[2:3], v[132:133] op_sel_hi:[1,0]
	v_mul_f32_e32 v133, 0xbfb8aa3b, v139
	v_exp_f32_e32 v133, v133
	s_nop 0
	v_add_f32_e32 v133, 1.0, v133
	v_rcp_f32_e32 v141, v133
	s_nop 0
	v_pk_mul_f32 v[138:139], v[138:139], v[140:141]
	v_pk_mul_f32 v[140:141], v[20:21], v[132:133] op_sel_hi:[1,0]
	v_pk_mul_f32 v[138:139], v[142:143], v[138:139]
	v_mul_f32_e32 v133, 0xbfb8aa3b, v140
	v_mul_f32_e32 v143, 0xbfb8aa3b, v141
	v_exp_f32_e32 v133, v133
	v_exp_f32_e32 v143, v143
	v_add_f32_e32 v133, 1.0, v133
	v_add_f32_e32 v143, 1.0, v143
	v_rcp_f32_e32 v142, v133
	v_rcp_f32_e32 v143, v143
	v_pk_mul_f32 v[132:133], v[4:5], v[132:133] op_sel_hi:[1,0]
	v_pk_mul_f32 v[140:141], v[140:141], v[142:143]
	s_nop 0
	v_pk_mul_f32 v[140:141], v[132:133], v[140:141]
	v_cvt_pk_bf16_f32 v132, v134, v135
	v_cvt_pk_bf16_f32 v133, v136, v137
	v_cvt_pk_bf16_f32 v134, v138, v139
	v_cvt_pk_bf16_f32 v135, v140, v141
	global_store_dwordx4 v[130:131], v[132:135], off

; __device__ __forceinline__ void row_rstd8(const float* ssp, int row0, int fq, float (&rs)[2][4]) {
; #pragma unroll
;     for (int ai = 0; ai < 2; ++ai) {
;         f32x4 a[4], b[4];
; #pragma unroll
;         for (int m = 0; m < 4; ++m) { const float* q = ssp + (size_t)(row0 + ai * HALF + m * 16) * 32 + fq * 8; a[m] = *(const f32x4*)q; b[m] = *(const f32x4*)(q + 4); }
; #pragma unroll
;         for (int m = 0; m < 4; ++m) {
;             float s = ((a[m][0] + a[m][1]) + (a[m][2] + a[m][3])) + ((b[m][0] + b[m][1]) + (b[m][2] + b[m][3]));
;             s += __shfl_xor(s, 16); s += __shfl_xor(s, 32);
;             rs[ai][m] = rsqrtf(s * (1.0f / D) + 1e-6f);
;         }
;     }
; }
;     __device__ __forceinline__ void plain(const f32x4 (&acc)[2][2][4][2], bf16_t* base, int ld, int colbase, int row0, int cl) const {
;         const int fq = (cl >> 3) & 3;
;         const float* ssin = (const float*)(ws + OFF_SUMSQ) + (size_t)ssi * SS_SLOT;
;         float rsv[2][4];
;         row_rstd8(ssin, row0, fq, rsv);
; #pragma unroll
;         for (int ai = 0; ai < 2; ++ai)
; #pragma unroll
;             for (int m = 0; m < 4; ++m) {
;                 const int row = row0 + ai * HALF + m * 16;
;                 const float rs = rsv[ai][m];
;                 bf16_t* rp = base + (size_t)row * ld + colbase + cl;
.LBB0_596:
	v_cmp_lt_i32_e32 vcc, v232, v231
	v_ashrrev_i32_e32 v163, 31, v162
	v_or_b32_e32 v168, 16, v162
	v_cndmask_b32_e32 v130, v229, v232, vcc
	v_cmp_lt_i32_e32 vcc, v230, v231
	v_lshlrev_b32_e32 v173, 2, v130
	v_ashrrev_i32_e32 v169, 31, v168
	v_cndmask_b32_e32 v130, v229, v230, vcc
	v_lshlrev_b32_e32 v171, 2, v130
	s_waitcnt lgkmcnt(0)
	v_lshlrev_b64 v[130:131], 7, v[162:163]
	v_lshl_add_u64 v[134:135], v[190:191], 0, v[130:131]
	s_nop 0
	s_nop 0
	s_nop 0
	v_lshlrev_b64 v[138:139], 7, v[168:169]
	v_lshl_add_u64 v[142:143], v[190:191], 0, v[138:139]
	s_nop 0
	s_nop 0
	s_nop 0
	v_or_b32_e32 v166, 32, v162
	v_ashrrev_i32_e32 v167, 31, v166
	v_lshlrev_b64 v[146:147], 7, v[166:167]
	v_or_b32_e32 v164, 48, v162
	v_lshl_add_u64 v[150:151], v[190:191], 0, v[146:147]
	v_ashrrev_i32_e32 v165, 31, v164
	s_nop 0
	s_nop 0
	s_nop 0
	v_lshlrev_b64 v[154:155], 7, v[164:165]
	v_lshl_add_u64 v[158:159], v[190:191], 0, v[154:155]
	s_nop 0
	s_nop 0
	s_nop 0
	s_mov_b32 s30, 0x358637bd
	s_lshl_b64 s[44:45], s[44:45], 1
	v_mov_b64_e32 v[202:203], s[30:31]
	s_add_u32 s57, s26, s44
	s_addc_u32 s83, s27, s45
	v_add_u32_e32 v210, 0x80, v162
	v_ashrrev_i32_e32 v211, 31, v210
	v_add_u32_e32 v208, 0x90, v162
	v_ashrrev_i32_e32 v209, 31, v208
	v_add_u32_e32 v206, 0xa0, v162
	v_ashrrev_i32_e32 v207, 31, v206
	v_add_u32_e32 v204, 0xb0, v162
	v_ashrrev_i32_e32 v205, 31, v204
	s_ashr_i32 s61, s60, 31
	s_nop 0
	v_mov_b32_e32 v174, v130
	v_mov_b32_e32 v175, v134
	v_mov_b32_e32 v134, v131
	v_pk_add_f32 v[130:131], v[174:175], v[134:135]
	v_mov_b32_e32 v134, v132
	v_mov_b32_e32 v135, v136
	v_mov_b32_e32 v136, v133
	v_pk_add_f32 v[132:133], v[134:135], v[136:137]
	v_mov_b32_e32 v134, v140
	v_pk_add_f32 v[130:131], v[130:131], v[132:133]
	v_mov_b32_e32 v132, v138
	v_mov_b32_e32 v133, v142
	v_mov_b32_e32 v142, v139
	v_mov_b32_e32 v135, v144
	v_mov_b32_e32 v144, v141
	v_pk_add_f32 v[132:133], v[132:133], v[142:143]
	v_pk_add_f32 v[134:135], v[134:135], v[144:145]
	s_nop 0
	v_pk_add_f32 v[132:133], v[132:133], v[134:135]
	v_mov_b32_e32 v135, v130
	v_mov_b32_e32 v134, v132
	v_mov_b32_e32 v130, v133
	v_pk_add_f32 v[130:131], v[134:135], v[130:131]
	s_nop 0
	s_nop 0
	v_mov_b32_e32 v134, v156
	v_mov_b32_e32 v135, v160
	v_mov_b32_e32 v160, v157
	v_pk_add_f32 v[134:135], v[134:135], v[160:161]
	s_waitcnt lgkmcnt(0)
	v_pk_add_f32 v[130:131], v[130:131], v[132:133]
	s_nop 0
	s_nop 0
	s_waitcnt lgkmcnt(0)
	v_pk_add_f32 v[130:131], v[130:131], v[132:133]
	s_nop 0
	v_pk_fma_f32 v[130:131], v[130:131], s[22:23], v[202:203] op_sel_hi:[1,0,0]
	v_mov_b32_e32 v133, v152
	v_mul_f32_e32 v132, 0x4b800000, v131
	v_cmp_gt_f32_e64 s[44:45], s23, v131
	v_cmp_gt_f32_e32 vcc, s23, v130
	v_mov_b32_e32 v152, v149
	v_cndmask_b32_e64 v131, v131, v132, s[44:45]
	v_rsq_f32_e32 v131, v131
	s_nop 0
	v_mul_f32_e32 v132, 0x45800000, v131
	v_cndmask_b32_e64 v176, v131, v132, s[44:45]
	ds_read_b32 v176, v242 offset:0
	v_mul_f32_e32 v131, 0x4b800000, v130
	v_cndmask_b32_e32 v130, v130, v131, vcc
	v_rsq_f32_e32 v130, v130
	v_mov_b32_e32 v132, v148
	v_pk_add_f32 v[132:133], v[132:133], v[152:153]
	v_mul_f32_e32 v131, 0x45800000, v130
	v_cndmask_b32_e32 v174, v130, v131, vcc
	ds_read_b32 v174, v242 offset:64
	v_mov_b32_e32 v130, v146
	v_mov_b32_e32 v131, v150
	v_mov_b32_e32 v150, v147
	v_pk_add_f32 v[130:131], v[130:131], v[150:151]
	s_nop 0
	v_pk_add_f32 v[130:131], v[130:131], v[132:133]
	v_mov_b32_e32 v132, v154
	v_mov_b32_e32 v133, v158
	v_mov_b32_e32 v158, v155
	v_pk_add_f32 v[132:133], v[132:133], v[158:159]
	v_lshlrev_b64 v[154:155], 7, v[204:205]
	v_pk_add_f32 v[132:133], v[132:133], v[134:135]
	v_mov_b32_e32 v135, v130
	v_mov_b32_e32 v134, v132
	v_mov_b32_e32 v130, v133
	v_pk_add_f32 v[130:131], v[134:135], v[130:131]
	s_nop 0
	s_nop 0
	v_lshl_add_u64 v[154:155], v[190:191], 0, v[154:155]
	s_waitcnt lgkmcnt(0)
	v_pk_add_f32 v[130:131], v[130:131], v[132:133]
	s_nop 0
	s_nop 0
	s_waitcnt lgkmcnt(0)
	v_pk_add_f32 v[130:131], v[130:131], v[132:133]
	s_nop 0
	v_pk_fma_f32 v[130:131], v[130:131], s[22:23], v[202:203] op_sel_hi:[1,0,0]
	s_nop 0
	v_mul_f32_e32 v132, 0x4b800000, v131
	v_cmp_gt_f32_e64 s[44:45], s23, v131
	v_cmp_gt_f32_e32 vcc, s23, v130
	s_nop 0
	v_cndmask_b32_e64 v131, v131, v132, s[44:45]
	v_rsq_f32_e32 v131, v131
	s_nop 0
	v_mul_f32_e32 v132, 0x45800000, v131
	v_cndmask_b32_e64 v172, v131, v132, s[44:45]
	ds_read_b32 v172, v242 offset:128
	v_mul_f32_e32 v131, 0x4b800000, v130
	v_cndmask_b32_e32 v130, v130, v131, vcc
	v_rsq_f32_e32 v130, v130
	s_nop 0
	v_mul_f32_e32 v131, 0x45800000, v130
	v_cndmask_b32_e32 v170, v130, v131, vcc
	ds_read_b32 v170, v242 offset:192
	v_lshlrev_b64 v[130:131], 7, v[210:211]
	v_lshl_add_u64 v[130:131], v[190:191], 0, v[130:131]
	s_nop 0
	s_nop 0
	v_lshlrev_b64 v[130:131], 7, v[208:209]
	v_lshl_add_u64 v[130:131], v[190:191], 0, v[130:131]
	s_nop 0
	s_nop 0
	v_lshlrev_b64 v[130:131], 7, v[206:207]
	v_lshl_add_u64 v[130:131], v[190:191], 0, v[130:131]
	s_nop 0
	s_nop 0
	s_nop 0
	s_nop 0
	s_nop 0
	s_nop 0
	s_nop 0
	s_nop 0
	v_mov_b32_e32 v212, v142
	s_nop 0
	v_mov_b32_e32 v213, v138
	v_mov_b32_e32 v138, v143
	v_mov_b32_e32 v142, v144
	v_mov_b32_e32 v143, v140
	v_mov_b32_e32 v140, v145
	v_pk_add_f32 v[138:139], v[212:213], v[138:139]
	v_pk_add_f32 v[140:141], v[142:143], v[140:141]
	s_nop 0
	v_mov_b32_e32 v142, v152
	v_pk_add_f32 v[138:139], v[138:139], v[140:141]
	v_mov_b32_e32 v140, v150
	s_nop 0
	v_mov_b32_e32 v141, v146
	v_mov_b32_e32 v146, v151
	v_mov_b32_e32 v143, v148
	v_mov_b32_e32 v148, v153
	v_pk_add_f32 v[140:141], v[140:141], v[146:147]
	v_pk_add_f32 v[142:143], v[142:143], v[148:149]
	s_waitcnt lgkmcnt(0)
; __device__ __forceinline__ unsigned cvt_pk_bf16(float lo, float hi) { const f32x2_t v = {lo, hi}; return __builtin_bit_cast(unsigned, __builtin_convertvector(v, bf16x2_t)); }
;     __device__ __forceinline__ void plain(const f32x4 (&acc)[2][2][4][2], bf16_t* base, int ld, int colbase, int row0, int cl) const {
;         const int fq = (cl >> 3) & 3;
;         const float* ssin = (const float*)(ws + OFF_SUMSQ) + (size_t)ssi * SS_SLOT;
;         float rsv[2][4];
;         row_rstd8(ssin, row0, fq, rsv);
; #pragma unroll
;         for (int ai = 0; ai < 2; ++ai)
; #pragma unroll
;             for (int m = 0; m < 4; ++m) {
;                 const int row = row0 + ai * HALF + m * 16;
;                 const float rs = rsv[ai][m];
;                 bf16_t* rp = base + (size_t)row * ld + colbase + cl;
; #pragma unroll
;                 for (int bj = 0; bj < 2; ++bj) {
;                     const f32x4 v0 = acc[ai][bj][m][0] * rs, v1 = acc[ai][bj][m][1] * rs;
;                     u32x4 w; w.x = cvt_pk_bf16(v0[0], v0[1]); w.y = cvt_pk_bf16(v0[2], v0[3]); w.z = cvt_pk_bf16(v1[0], v1[1]); w.w = cvt_pk_bf16(v1[2], v1[3]);
;                     *(u32x4*)(rp + bj * HALF) = w;
;                 }
;             }
	v_pk_mul_f32 v[144:145], v[128:129], v[176:177] op_sel_hi:[1,0]
	v_pk_add_f32 v[140:141], v[140:141], v[142:143]
	v_mov_b32_e32 v143, v138
	v_mov_b32_e32 v142, v140
	v_mov_b32_e32 v138, v141
	v_pk_add_f32 v[138:139], v[142:143], v[138:139]
	s_nop 0
	s_nop 0
	s_nop 0
	v_mov_b32_e32 v142, v134
	s_nop 0
	v_mov_b32_e32 v143, v130
	v_mov_b32_e32 v130, v135
	v_mov_b32_e32 v134, v136
	v_mov_b32_e32 v135, v132
	v_mov_b32_e32 v132, v137
	v_pk_add_f32 v[130:131], v[142:143], v[130:131]
	v_pk_add_f32 v[132:133], v[134:135], v[132:133]
	s_nop 0
	v_mov_b32_e32 v134, v160
	v_pk_add_f32 v[130:131], v[130:131], v[132:133]
	v_mov_b32_e32 v132, v158
	s_nop 0
	v_mov_b32_e32 v133, v154
	v_mov_b32_e32 v154, v159
	v_mov_b32_e32 v135, v156
	v_mov_b32_e32 v156, v161
	v_pk_add_f32 v[132:133], v[132:133], v[154:155]
	v_pk_add_f32 v[134:135], v[134:135], v[156:157]
	s_waitcnt lgkmcnt(0)
	v_pk_add_f32 v[138:139], v[138:139], v[140:141]
	v_pk_add_f32 v[132:133], v[132:133], v[134:135]
	v_mov_b32_e32 v135, v130
	v_mov_b32_e32 v134, v132
	v_mov_b32_e32 v130, v133
	s_nop 0
	s_nop 0
	v_pk_add_f32 v[130:131], v[134:135], v[130:131]
	s_nop 0
	s_nop 0
	v_pk_mul_f32 v[142:143], v[126:127], v[176:177] op_sel_hi:[1,0]
	s_waitcnt lgkmcnt(2)
	v_pk_add_f32 v[138:139], v[138:139], v[140:141]
	v_pk_mul_f32 v[146:147], v[124:125], v[176:177] op_sel_hi:[1,0]
	v_pk_fma_f32 v[138:139], v[138:139], s[22:23], v[202:203] op_sel_hi:[1,0,0]
	s_waitcnt lgkmcnt(0)
	v_pk_add_f32 v[130:131], v[130:131], v[132:133]
	v_mul_f32_e32 v140, 0x4b800000, v139
	v_cmp_gt_f32_e64 s[44:45], s23, v139
	s_nop 0
	s_nop 0
	v_cndmask_b32_e64 v139, v139, v140, s[44:45]
	v_rsq_f32_e32 v139, v139
	v_pk_mul_f32 v[148:149], v[122:123], v[176:177] op_sel_hi:[1,0]
	v_cvt_pk_bf16_f32 v142, v142, v143
	s_waitcnt lgkmcnt(0)
	v_pk_add_f32 v[130:131], v[130:131], v[132:133]
	v_mul_f32_e32 v140, 0x45800000, v139
	v_pk_fma_f32 v[130:131], v[130:131], s[22:23], v[202:203] op_sel_hi:[1,0,0]
	v_cndmask_b32_e64 v140, v139, v140, s[44:45]
	ds_read_b32 v140, v242 offset:512
	v_mul_f32_e32 v132, 0x4b800000, v131
	v_cmp_gt_f32_e64 s[44:45], s23, v131
	v_cvt_pk_bf16_f32 v143, v144, v145
	v_cvt_pk_bf16_f32 v144, v148, v149
	v_cndmask_b32_e64 v131, v131, v132, s[44:45]
	v_rsq_f32_e32 v131, v131
	v_cvt_pk_bf16_f32 v145, v146, v147
	v_pk_mul_f32 v[146:147], v[108:109], v[176:177] op_sel_hi:[1,0]
	v_pk_mul_f32 v[148:149], v[106:107], v[176:177] op_sel_hi:[1,0]
	v_mul_f32_e32 v132, 0x45800000, v131
	v_cndmask_b32_e64 v132, v131, v132, s[44:45]
	ds_read_b32 v132, v242 offset:640
	s_lshl_b64 s[44:45], s[60:61], 1
	s_add_u32 s44, s57, s44
	s_addc_u32 s45, s83, s45
	v_lshl_add_u64 v[134:135], s[44:45], 0, v[0:1]
	v_mad_i64_i32 v[136:137], s[44:45], s56, v162, 0
	v_lshl_add_u64 v[136:137], v[136:137], 1, v[134:135]
	global_store_dwordx4 v[136:137], v[142:145], off
	v_cmp_gt_f32_e32 vcc, s23, v138
	v_mul_f32_e32 v139, 0x4b800000, v138
	v_pk_mul_f32 v[144:145], v[116:117], v[176:177] op_sel_hi:[1,0]
	v_pk_mul_f32 v[142:143], v[114:115], v[176:177] op_sel_hi:[1,0]
	v_cndmask_b32_e32 v138, v138, v139, vcc
	v_cvt_pk_bf16_f32 v142, v142, v143
	v_cvt_pk_bf16_f32 v143, v144, v145
	v_cvt_pk_bf16_f32 v144, v148, v149
	v_cvt_pk_bf16_f32 v145, v146, v147
	global_store_dwordx4 v[136:137], v[142:145], off offset:256
	v_mad_i64_i32 v[136:137], s[44:45], s56, v168, 0
	s_nop 0
	s_waitcnt lgkmcnt(0)
	v_pk_mul_f32 v[144:145], v[120:121], v[174:175] op_sel_hi:[1,0]
	v_pk_mul_f32 v[142:143], v[118:119], v[174:175] op_sel_hi:[1,0]
	v_pk_mul_f32 v[146:147], v[112:113], v[174:175] op_sel_hi:[1,0]
	v_pk_mul_f32 v[148:149], v[110:111], v[174:175] op_sel_hi:[1,0]
	v_lshl_add_u64 v[136:137], v[136:137], 1, v[134:135]
	v_cvt_pk_bf16_f32 v142, v142, v143
	v_cvt_pk_bf16_f32 v143, v144, v145
	v_cvt_pk_bf16_f32 v144, v148, v149
	v_cvt_pk_bf16_f32 v145, v146, v147
	global_store_dwordx4 v[136:137], v[142:145], off
	v_pk_mul_f32 v[146:147], v[92:93], v[174:175] op_sel_hi:[1,0]
	v_pk_mul_f32 v[148:149], v[90:91], v[174:175] op_sel_hi:[1,0]
	v_pk_mul_f32 v[144:145], v[100:101], v[174:175] op_sel_hi:[1,0]
	v_pk_mul_f32 v[142:143], v[98:99], v[174:175] op_sel_hi:[1,0]
	v_rsq_f32_e32 v138, v138
	v_cvt_pk_bf16_f32 v142, v142, v143
	v_cvt_pk_bf16_f32 v143, v144, v145
	v_cvt_pk_bf16_f32 v144, v148, v149
	v_cvt_pk_bf16_f32 v145, v146, v147
	global_store_dwordx4 v[136:137], v[142:145], off offset:256
	v_mad_i64_i32 v[136:137], s[44:45], s56, v166, 0
	s_nop 0
	s_waitcnt lgkmcnt(0)
	v_pk_mul_f32 v[144:145], v[104:105], v[172:173] op_sel_hi:[1,0]
	v_pk_mul_f32 v[142:143], v[102:103], v[172:173] op_sel_hi:[1,0]
	v_pk_mul_f32 v[146:147], v[96:97], v[172:173] op_sel_hi:[1,0]
	v_pk_mul_f32 v[148:149], v[94:95], v[172:173] op_sel_hi:[1,0]
	v_lshl_add_u64 v[136:137], v[136:137], 1, v[134:135]
	v_cvt_pk_bf16_f32 v142, v142, v143
	v_cvt_pk_bf16_f32 v143, v144, v145
	v_cvt_pk_bf16_f32 v144, v148, v149
	v_cvt_pk_bf16_f32 v145, v146, v147
	global_store_dwordx4 v[136:137], v[142:145], off
	v_pk_mul_f32 v[146:147], v[76:77], v[172:173] op_sel_hi:[1,0]
	v_pk_mul_f32 v[148:149], v[74:75], v[172:173] op_sel_hi:[1,0]
	v_pk_mul_f32 v[144:145], v[84:85], v[172:173] op_sel_hi:[1,0]
	v_pk_mul_f32 v[142:143], v[82:83], v[172:173] op_sel_hi:[1,0]
	v_mul_f32_e32 v139, 0x45800000, v138
	v_cvt_pk_bf16_f32 v142, v142, v143
	v_cvt_pk_bf16_f32 v143, v144, v145
	v_cvt_pk_bf16_f32 v144, v148, v149
	v_cvt_pk_bf16_f32 v145, v146, v147
	global_store_dwordx4 v[136:137], v[142:145], off offset:256
	v_mad_i64_i32 v[136:137], s[44:45], s56, v164, 0
	s_nop 0
	s_waitcnt lgkmcnt(0)
; __device__ __forceinline__ unsigned cvt_pk_bf16(float lo, float hi) { const f32x2_t v = {lo, hi}; return __builtin_bit_cast(unsigned, __builtin_convertvector(v, bf16x2_t)); }
;     __device__ __forceinline__ void plain(const f32x4 (&acc)[2][2][4][2], bf16_t* base, int ld, int colbase, int row0, int cl) const {
;     ...
;             for (int m = 0; m < 4; ++m) {
;                 const int row = row0 + ai * HALF + m * 16;
;                 const float rs = rsv[ai][m];
;                 bf16_t* rp = base + (size_t)row * ld + colbase + cl;
; #pragma unroll
;                 for (int bj = 0; bj < 2; ++bj) {
;                     const f32x4 v0 = acc[ai][bj][m][0] * rs, v1 = acc[ai][bj][m][1] * rs;
;                     u32x4 w; w.x = cvt_pk_bf16(v0[0], v0[1]); w.y = cvt_pk_bf16(v0[2], v0[3]); w.z = cvt_pk_bf16(v1[0], v1[1]); w.w = cvt_pk_bf16(v1[2], v1[3]);
;                     *(u32x4*)(rp + bj * HALF) = w;
;                 }
;             }
	v_pk_mul_f32 v[144:145], v[88:89], v[170:171] op_sel_hi:[1,0]
	v_pk_mul_f32 v[142:143], v[86:87], v[170:171] op_sel_hi:[1,0]
	v_pk_mul_f32 v[146:147], v[80:81], v[170:171] op_sel_hi:[1,0]
	v_pk_mul_f32 v[148:149], v[78:79], v[170:171] op_sel_hi:[1,0]
	v_lshl_add_u64 v[136:137], v[136:137], 1, v[134:135]
	v_cvt_pk_bf16_f32 v142, v142, v143
	v_cvt_pk_bf16_f32 v143, v144, v145
	v_cvt_pk_bf16_f32 v144, v148, v149
	v_cvt_pk_bf16_f32 v145, v146, v147
	global_store_dwordx4 v[136:137], v[142:145], off
	v_pk_mul_f32 v[146:147], v[68:69], v[170:171] op_sel_hi:[1,0]
	v_pk_mul_f32 v[148:149], v[66:67], v[170:171] op_sel_hi:[1,0]
	v_pk_mul_f32 v[144:145], v[72:73], v[170:171] op_sel_hi:[1,0]
	v_pk_mul_f32 v[142:143], v[70:71], v[170:171] op_sel_hi:[1,0]
	v_cndmask_b32_e32 v138, v138, v139, vcc
	ds_read_b32 v138, v242 offset:576
	v_cvt_pk_bf16_f32 v142, v142, v143
	v_cvt_pk_bf16_f32 v143, v144, v145
	v_cvt_pk_bf16_f32 v144, v148, v149
	v_cvt_pk_bf16_f32 v145, v146, v147
	global_store_dwordx4 v[136:137], v[142:145], off offset:256
	v_mad_i64_i32 v[136:137], s[44:45], s56, v210, 0
	s_nop 0
	s_waitcnt lgkmcnt(0)
	v_pk_mul_f32 v[144:145], v[64:65], v[140:141] op_sel_hi:[1,0]
	v_pk_mul_f32 v[142:143], v[62:63], v[140:141] op_sel_hi:[1,0]
	v_pk_mul_f32 v[146:147], v[60:61], v[140:141] op_sel_hi:[1,0]
	v_pk_mul_f32 v[148:149], v[58:59], v[140:141] op_sel_hi:[1,0]
	v_lshl_add_u64 v[136:137], v[136:137], 1, v[134:135]
	v_cvt_pk_bf16_f32 v142, v142, v143
	v_cvt_pk_bf16_f32 v143, v144, v145
	v_cvt_pk_bf16_f32 v144, v148, v149
	v_cvt_pk_bf16_f32 v145, v146, v147
	global_store_dwordx4 v[136:137], v[142:145], off
	v_pk_mul_f32 v[146:147], v[44:45], v[140:141] op_sel_hi:[1,0]
	v_pk_mul_f32 v[148:149], v[42:43], v[140:141] op_sel_hi:[1,0]
	v_pk_mul_f32 v[142:143], v[48:49], v[140:141] op_sel_hi:[1,0]
	v_pk_mul_f32 v[144:145], v[46:47], v[140:141] op_sel_hi:[1,0]
	v_cvt_pk_bf16_f32 v141, v142, v143
	v_cvt_pk_bf16_f32 v140, v144, v145
	v_cvt_pk_bf16_f32 v142, v148, v149
	v_cvt_pk_bf16_f32 v143, v146, v147
	global_store_dwordx4 v[136:137], v[140:143], off offset:256
	v_mad_i64_i32 v[136:137], s[44:45], s56, v208, 0
	v_lshl_add_u64 v[144:145], v[136:137], 1, v[134:135]
	s_waitcnt lgkmcnt(0)
	v_pk_mul_f32 v[136:137], v[56:57], v[138:139] op_sel_hi:[1,0]
	v_pk_mul_f32 v[140:141], v[54:55], v[138:139] op_sel_hi:[1,0]
	v_pk_mul_f32 v[146:147], v[52:53], v[138:139] op_sel_hi:[1,0]
	v_pk_mul_f32 v[142:143], v[50:51], v[138:139] op_sel_hi:[1,0]
	v_cmp_gt_f32_e32 vcc, s23, v130
	v_mul_f32_e32 v131, 0x4b800000, v130
	v_cvt_pk_bf16_f32 v140, v140, v141
	v_cvt_pk_bf16_f32 v141, v136, v137
	v_cvt_pk_bf16_f32 v142, v142, v143
	v_cvt_pk_bf16_f32 v143, v146, v147
	v_cndmask_b32_e32 v130, v130, v131, vcc
	global_store_dwordx4 v[144:145], v[140:143], off
	v_pk_mul_f32 v[136:137], v[30:31], v[138:139] op_sel_hi:[1,0]
	v_rsq_f32_e32 v130, v130
	v_pk_mul_f32 v[140:141], v[32:33], v[138:139] op_sel_hi:[1,0]
	v_pk_mul_f32 v[142:143], v[28:29], v[138:139] op_sel_hi:[1,0]
	v_pk_mul_f32 v[138:139], v[26:27], v[138:139] op_sel_hi:[1,0]
	v_cvt_pk_bf16_f32 v136, v136, v137
	v_cvt_pk_bf16_f32 v137, v140, v141
	v_cvt_pk_bf16_f32 v138, v138, v139
	v_cvt_pk_bf16_f32 v139, v142, v143
	global_store_dwordx4 v[144:145], v[136:139], off offset:256
	s_waitcnt lgkmcnt(0)
	v_pk_mul_f32 v[142:143], v[36:37], v[132:133] op_sel_hi:[1,0]
	v_pk_mul_f32 v[144:145], v[34:35], v[132:133] op_sel_hi:[1,0]
	v_mad_i64_i32 v[136:137], s[44:45], s56, v206, 0
	v_lshl_add_u64 v[140:141], v[136:137], 1, v[134:135]
	v_pk_mul_f32 v[138:139], v[40:41], v[132:133] op_sel_hi:[1,0]
	v_pk_mul_f32 v[136:137], v[38:39], v[132:133] op_sel_hi:[1,0]
	v_mul_f32_e32 v131, 0x45800000, v130
	v_cvt_pk_bf16_f32 v136, v136, v137
	v_cvt_pk_bf16_f32 v137, v138, v139
	v_cvt_pk_bf16_f32 v138, v144, v145
	v_cvt_pk_bf16_f32 v139, v142, v143
	global_store_dwordx4 v[140:141], v[136:139], off
	v_pk_mul_f32 v[142:143], v[12:13], v[132:133] op_sel_hi:[1,0]
	v_cndmask_b32_e32 v130, v130, v131, vcc
	ds_read_b32 v130, v242 offset:704
	v_pk_mul_f32 v[138:139], v[16:17], v[132:133] op_sel_hi:[1,0]
	v_pk_mul_f32 v[136:137], v[14:15], v[132:133] op_sel_hi:[1,0]
	v_pk_mul_f32 v[132:133], v[10:11], v[132:133] op_sel_hi:[1,0]
	v_cvt_pk_bf16_f32 v136, v136, v137
	v_cvt_pk_bf16_f32 v137, v138, v139
	v_cvt_pk_bf16_f32 v138, v132, v133
	v_cvt_pk_bf16_f32 v139, v142, v143
	v_mad_i64_i32 v[132:133], s[44:45], s56, v204, 0
	global_store_dwordx4 v[140:141], v[136:139], off offset:256
	s_waitcnt lgkmcnt(0)
	v_pk_mul_f32 v[140:141], v[18:19], v[130:131] op_sel_hi:[1,0]
	s_nop 0
	v_lshl_add_u64 v[136:137], v[132:133], 1, v[134:135]
	v_pk_mul_f32 v[134:135], v[24:25], v[130:131] op_sel_hi:[1,0]
	v_pk_mul_f32 v[132:133], v[22:23], v[130:131] op_sel_hi:[1,0]
	v_pk_mul_f32 v[138:139], v[20:21], v[130:131] op_sel_hi:[1,0]
	v_cvt_pk_bf16_f32 v132, v132, v133
	v_cvt_pk_bf16_f32 v133, v134, v135
	v_cvt_pk_bf16_f32 v134, v140, v141
	v_cvt_pk_bf16_f32 v135, v138, v139
	global_store_dwordx4 v[136:137], v[132:135], off
	v_pk_mul_f32 v[138:139], v[4:5], v[130:131] op_sel_hi:[1,0]
	v_pk_mul_f32 v[140:141], v[2:3], v[130:131] op_sel_hi:[1,0]
	v_pk_mul_f32 v[132:133], v[8:9], v[130:131] op_sel_hi:[1,0]
	v_pk_mul_f32 v[134:135], v[6:7], v[130:131] op_sel_hi:[1,0]
	v_cvt_pk_bf16_f32 v131, v132, v133
	v_cvt_pk_bf16_f32 v130, v134, v135
	v_cvt_pk_bf16_f32 v132, v140, v141
	v_cvt_pk_bf16_f32 v133, v138, v139
	global_store_dwordx4 v[136:137], v[130:133], off offset:256
; __device__ __forceinline__ float row_rstd(const float* ssp, int row, int fq) {
;     const f32x4 a = *(const f32x4*)(ssp + (size_t)row * 32 + fq * 8), b = *(const f32x4*)(ssp + (size_t)row * 32 + fq * 8 + 4);
;     float s = ((a[0] + a[1]) + (a[2] + a[3])) + ((b[0] + b[1]) + (b[2] + b[3]));
;     s += __shfl_xor(s, 16); s += __shfl_xor(s, 32);
;     return rsqrtf(s * (1.0f / D) + 1e-6f);
; }
;     __device__ __forceinline__ void operator()(const f32x4 (&acc)[2][2][4][2], const Unit& u, int wr, int wc, int fr, int fq) const {
;     ...
;             else {
;                 const float* ssin = (const float*)(ws + OFF_SUMSQ) + (size_t)ssi * SS_SLOT;
;                 float* f0 = (float*)(tmp + TG_Z);
; #pragma unroll
;                 for (int ai = 0; ai < 2; ++ai)
; #pragma unroll
;                     for (int m = 0; m < 4; ++m) {
;                         const int row = row0 + ai * HALF + m * 16;
;                         const float rs = row_rstd(ssin, row, fq);
;                         if (wc == 0 && fq < 2) {
;                             *(f32x4*)(f0 + (size_t)row * 16 + 8 * fq) = acc[ai][0][m][0] * rs;
;                             *(f32x4*)(f0 + (size_t)row * 16 + 8 * fq + 4) = acc[ai][0][m][1] * rs;
;                         }
;                     }
.LBB0_597:
	s_and_b64 vcc, exec, s[58:59]
	s_cbranch_vccz .LBB0_618
	v_cmp_lt_i32_e32 vcc, v232, v231
	s_cmp_gt_i32 s82, 23
	s_mov_b64 s[44:45], -1
	v_cndmask_b32_e32 v130, v229, v232, vcc
	v_cmp_lt_i32_e32 vcc, v230, v231
	v_lshlrev_b32_e32 v173, 2, v130
	s_nop 0
	v_cndmask_b32_e32 v130, v229, v230, vcc
	v_lshlrev_b32_e32 v171, 2, v130
	s_cbranch_scc0 .LBB0_616
	v_ashrrev_i32_e32 v163, 31, v162
	s_waitcnt lgkmcnt(0)
	v_lshlrev_b64 v[130:131], 7, v[162:163]
	v_lshl_add_u64 v[134:135], v[190:191], 0, v[130:131]
	s_nop 0
	s_nop 0
	s_nop 0
	s_nop 0
	v_add_f32_e32 v130, v130, v131
	v_add_f32_e32 v131, v132, v133
	v_add_f32_e32 v132, v134, v135
	v_add_f32_e32 v133, v136, v137
	v_add_f32_e32 v130, v130, v131
	v_add_f32_e32 v131, v132, v133
	v_add_f32_e32 v130, v130, v131
	s_nop 0
	s_waitcnt lgkmcnt(0)
	v_add_f32_e32 v130, v130, v131
	s_nop 0
	s_and_saveexec_b64 s[44:45], s[52:53]
	s_cbranch_execz .LBB0_601
	s_waitcnt lgkmcnt(0)
	v_add_f32_e32 v130, v130, v131
	v_fmamk_f32 v130, v130, 0x3a000000, v225
	v_mul_f32_e32 v131, 0x4b800000, v130
	v_cmp_gt_f32_e32 vcc, s23, v130
	v_lshlrev_b64 v[134:135], 6, v[162:163]
	v_lshl_add_u64 v[134:135], v[192:193], 0, v[134:135]
	v_cndmask_b32_e32 v130, v130, v131, vcc
	v_rsq_f32_e32 v130, v130
	s_nop 0
	v_mul_f32_e32 v131, 0x45800000, v130
	v_cndmask_b32_e32 v136, v130, v131, vcc
	ds_read_b32 v136, v242 offset:0
	s_waitcnt lgkmcnt(0)
	v_pk_mul_f32 v[132:133], v[128:129], v[136:137] op_sel_hi:[1,0]
	v_pk_mul_f32 v[130:131], v[126:127], v[136:137] op_sel_hi:[1,0]
	global_store_dwordx4 v[134:135], v[130:133], off
	s_nop 1
	v_pk_mul_f32 v[132:133], v[124:125], v[136:137] op_sel_hi:[1,0]
	v_pk_mul_f32 v[130:131], v[122:123], v[136:137] op_sel_hi:[1,0]
	global_store_dwordx4 v[134:135], v[130:133], off offset:16
.LBB0_601:
	s_or_b64 exec, exec, s[44:45]
	s_nop 0
	v_or_b32_e32 v130, 16, v162
	s_waitcnt lgkmcnt(0)
	v_ashrrev_i32_e32 v131, 31, v130
	v_lshlrev_b64 v[132:133], 7, v[130:131]
	v_lshl_add_u64 v[136:137], v[190:191], 0, v[132:133]
	s_nop 0
	s_nop 0
	s_nop 0
	s_nop 0
	v_add_f32_e32 v132, v132, v133
	v_add_f32_e32 v133, v134, v135
	s_nop 0
	v_add_f32_e32 v134, v136, v137
	v_add_f32_e32 v135, v138, v139
	v_add_f32_e32 v132, v132, v133
	v_add_f32_e32 v133, v134, v135
	v_add_f32_e32 v132, v132, v133
	s_nop 0
	s_waitcnt lgkmcnt(0)
	v_add_f32_e32 v132, v132, v133
	s_nop 0
	s_and_saveexec_b64 s[44:45], s[52:53]
	s_cbranch_execz .LBB0_603
	s_waitcnt lgkmcnt(0)
	v_add_f32_e32 v132, v132, v133
	v_fmamk_f32 v132, v132, 0x3a000000, v225
	v_mul_f32_e32 v133, 0x4b800000, v132
	v_cmp_gt_f32_e32 vcc, s23, v132
	v_lshlrev_b64 v[134:135], 6, v[130:131]
	v_lshl_add_u64 v[134:135], v[192:193], 0, v[134:135]
	v_cndmask_b32_e32 v132, v132, v133, vcc
	v_rsq_f32_e32 v132, v132
	s_nop 0
	v_mul_f32_e32 v130, 0x45800000, v132
	v_cndmask_b32_e32 v136, v132, v130, vcc
	ds_read_b32 v136, v242 offset:64
	s_waitcnt lgkmcnt(0)
	v_pk_mul_f32 v[132:133], v[120:121], v[136:137] op_sel_hi:[1,0]
	v_pk_mul_f32 v[130:131], v[118:119], v[136:137] op_sel_hi:[1,0]
	global_store_dwordx4 v[134:135], v[130:133], off
	s_nop 1
	v_pk_mul_f32 v[132:133], v[112:113], v[136:137] op_sel_hi:[1,0]
	v_pk_mul_f32 v[130:131], v[110:111], v[136:137] op_sel_hi:[1,0]
	global_store_dwordx4 v[134:135], v[130:133], off offset:16
.LBB0_603:
	s_or_b64 exec, exec, s[44:45]
	s_nop 0
	v_or_b32_e32 v130, 32, v162
	v_ashrrev_i32_e32 v131, 31, v130
	s_waitcnt lgkmcnt(0)
	v_lshlrev_b64 v[132:133], 7, v[130:131]
	v_lshl_add_u64 v[136:137], v[190:191], 0, v[132:133]
	s_nop 0
	s_nop 0
	s_nop 0
	s_nop 0
	v_add_f32_e32 v132, v132, v133
	v_add_f32_e32 v133, v134, v135
	s_nop 0
	v_add_f32_e32 v134, v136, v137
	v_add_f32_e32 v135, v138, v139
	v_add_f32_e32 v132, v132, v133
	v_add_f32_e32 v133, v134, v135
	v_add_f32_e32 v132, v132, v133
	s_nop 0
	s_waitcnt lgkmcnt(0)
	v_add_f32_e32 v132, v132, v133
	s_nop 0
	s_and_saveexec_b64 s[44:45], s[52:53]
	s_cbranch_execz .LBB0_605
	s_waitcnt lgkmcnt(0)
	v_add_f32_e32 v132, v132, v133
	v_fmamk_f32 v132, v132, 0x3a000000, v225
	v_mul_f32_e32 v133, 0x4b800000, v132
	v_cmp_gt_f32_e32 vcc, s23, v132
	v_lshlrev_b64 v[134:135], 6, v[130:131]
	v_lshl_add_u64 v[134:135], v[192:193], 0, v[134:135]
	v_cndmask_b32_e32 v132, v132, v133, vcc
	v_rsq_f32_e32 v132, v132
	s_nop 0
	v_mul_f32_e32 v130, 0x45800000, v132
	v_cndmask_b32_e32 v136, v132, v130, vcc
	ds_read_b32 v136, v242 offset:128
	s_waitcnt lgkmcnt(0)
	v_pk_mul_f32 v[132:133], v[104:105], v[136:137] op_sel_hi:[1,0]
	v_pk_mul_f32 v[130:131], v[102:103], v[136:137] op_sel_hi:[1,0]
	global_store_dwordx4 v[134:135], v[130:133], off
	s_nop 1
	v_pk_mul_f32 v[132:133], v[96:97], v[136:137] op_sel_hi:[1,0]
	v_pk_mul_f32 v[130:131], v[94:95], v[136:137] op_sel_hi:[1,0]
	global_store_dwordx4 v[134:135], v[130:133], off offset:16
.LBB0_605:
	s_or_b64 exec, exec, s[44:45]
	s_nop 0
	v_or_b32_e32 v130, 48, v162
	v_ashrrev_i32_e32 v131, 31, v130
	s_waitcnt lgkmcnt(0)
	v_lshlrev_b64 v[132:133], 7, v[130:131]
	v_lshl_add_u64 v[136:137], v[190:191], 0, v[132:133]
	s_nop 0
	s_nop 0
	s_nop 0
	s_nop 0
	v_add_f32_e32 v132, v132, v133
	v_add_f32_e32 v133, v134, v135
	s_nop 0
	v_add_f32_e32 v134, v136, v137
	v_add_f32_e32 v135, v138, v139
	v_add_f32_e32 v132, v132, v133
	v_add_f32_e32 v133, v134, v135
	v_add_f32_e32 v132, v132, v133
	s_nop 0
	s_waitcnt lgkmcnt(0)
	v_add_f32_e32 v132, v132, v133
	s_nop 0
	s_and_saveexec_b64 s[44:45], s[52:53]
	s_cbranch_execz .LBB0_607
	s_waitcnt lgkmcnt(0)
	v_add_f32_e32 v132, v132, v133
	v_fmamk_f32 v132, v132, 0x3a000000, v225
	v_mul_f32_e32 v133, 0x4b800000, v132
	v_cmp_gt_f32_e32 vcc, s23, v132
	v_lshlrev_b64 v[134:135], 6, v[130:131]
	v_lshl_add_u64 v[134:135], v[192:193], 0, v[134:135]
	v_cndmask_b32_e32 v132, v132, v133, vcc
	v_rsq_f32_e32 v132, v132
	s_nop 0
	v_mul_f32_e32 v130, 0x45800000, v132
	v_cndmask_b32_e32 v136, v132, v130, vcc
	ds_read_b32 v136, v242 offset:192
	s_waitcnt lgkmcnt(0)
	v_pk_mul_f32 v[132:133], v[88:89], v[136:137] op_sel_hi:[1,0]
	v_pk_mul_f32 v[130:131], v[86:87], v[136:137] op_sel_hi:[1,0]
	global_store_dwordx4 v[134:135], v[130:133], off
	s_nop 1
	v_pk_mul_f32 v[132:133], v[80:81], v[136:137] op_sel_hi:[1,0]
	v_pk_mul_f32 v[130:131], v[78:79], v[136:137] op_sel_hi:[1,0]
	global_store_dwordx4 v[134:135], v[130:133], off offset:16
; __device__ __forceinline__ float row_rstd(const float* ssp, int row, int fq) {
;     const f32x4 a = *(const f32x4*)(ssp + (size_t)row * 32 + fq * 8), b = *(const f32x4*)(ssp + (size_t)row * 32 + fq * 8 + 4);
;     float s = ((a[0] + a[1]) + (a[2] + a[3])) + ((b[0] + b[1]) + (b[2] + b[3]));
;     s += __shfl_xor(s, 16); s += __shfl_xor(s, 32);
;     return rsqrtf(s * (1.0f / D) + 1e-6f);
; }
;     __device__ __forceinline__ void operator()(const f32x4 (&acc)[2][2][4][2], const Unit& u, int wr, int wc, int fr, int fq) const {
;     ...
;             else {
;                 const float* ssin = (const float*)(ws + OFF_SUMSQ) + (size_t)ssi * SS_SLOT;
;                 float* f0 = (float*)(tmp + TG_Z);
; #pragma unroll
;                 for (int ai = 0; ai < 2; ++ai)
; #pragma unroll
;                     for (int m = 0; m < 4; ++m) {
;                         const int row = row0 + ai * HALF + m * 16;
;                         const float rs = row_rstd(ssin, row, fq);
;                         if (wc == 0 && fq < 2) {
;                             *(f32x4*)(f0 + (size_t)row * 16 + 8 * fq) = acc[ai][0][m][0] * rs;
;                             *(f32x4*)(f0 + (size_t)row * 16 + 8 * fq + 4) = acc[ai][0][m][1] * rs;
;                         }
;                     }
.LBB0_607:
	s_or_b64 exec, exec, s[44:45]
	s_nop 0
	v_add_u32_e32 v130, 0x80, v162
	v_ashrrev_i32_e32 v131, 31, v130
	s_waitcnt lgkmcnt(0)
	v_lshlrev_b64 v[132:133], 7, v[130:131]
	v_lshl_add_u64 v[136:137], v[190:191], 0, v[132:133]
	s_nop 0
	s_nop 0
	s_nop 0
	s_nop 0
	v_add_f32_e32 v132, v132, v133
	v_add_f32_e32 v133, v134, v135
	s_nop 0
	v_add_f32_e32 v134, v136, v137
	v_add_f32_e32 v135, v138, v139
	v_add_f32_e32 v132, v132, v133
	v_add_f32_e32 v133, v134, v135
	v_add_f32_e32 v132, v132, v133
	s_nop 0
	s_waitcnt lgkmcnt(0)
	v_add_f32_e32 v132, v132, v133
	s_nop 0
	s_and_saveexec_b64 s[44:45], s[52:53]
	s_cbranch_execz .LBB0_609
	s_waitcnt lgkmcnt(0)
	v_add_f32_e32 v132, v132, v133
	v_fmamk_f32 v132, v132, 0x3a000000, v225
	v_mul_f32_e32 v133, 0x4b800000, v132
	v_cmp_gt_f32_e32 vcc, s23, v132
	v_lshlrev_b64 v[134:135], 6, v[130:131]
	v_lshl_add_u64 v[134:135], v[192:193], 0, v[134:135]
	v_cndmask_b32_e32 v132, v132, v133, vcc
	v_rsq_f32_e32 v132, v132
	s_nop 0
	v_mul_f32_e32 v130, 0x45800000, v132
	v_cndmask_b32_e32 v136, v132, v130, vcc
	ds_read_b32 v136, v242 offset:512
	s_waitcnt lgkmcnt(0)
	v_pk_mul_f32 v[132:133], v[64:65], v[136:137] op_sel_hi:[1,0]
	v_pk_mul_f32 v[130:131], v[62:63], v[136:137] op_sel_hi:[1,0]
	global_store_dwordx4 v[134:135], v[130:133], off
	s_nop 1
	v_pk_mul_f32 v[132:133], v[60:61], v[136:137] op_sel_hi:[1,0]
	v_pk_mul_f32 v[130:131], v[58:59], v[136:137] op_sel_hi:[1,0]
	global_store_dwordx4 v[134:135], v[130:133], off offset:16
.LBB0_609:
	s_or_b64 exec, exec, s[44:45]
	s_nop 0
	v_add_u32_e32 v130, 0x90, v162
	v_ashrrev_i32_e32 v131, 31, v130
	s_waitcnt lgkmcnt(0)
	v_lshlrev_b64 v[132:133], 7, v[130:131]
	v_lshl_add_u64 v[136:137], v[190:191], 0, v[132:133]
	s_nop 0
	s_nop 0
	s_nop 0
	s_nop 0
	v_add_f32_e32 v132, v132, v133
	v_add_f32_e32 v133, v134, v135
	s_nop 0
	v_add_f32_e32 v134, v136, v137
	v_add_f32_e32 v135, v138, v139
	v_add_f32_e32 v132, v132, v133
	v_add_f32_e32 v133, v134, v135
	v_add_f32_e32 v132, v132, v133
	s_nop 0
	s_waitcnt lgkmcnt(0)
	v_add_f32_e32 v132, v132, v133
	s_nop 0
	s_and_saveexec_b64 s[44:45], s[52:53]
	s_cbranch_execz .LBB0_611
	s_waitcnt lgkmcnt(0)
	v_add_f32_e32 v132, v132, v133
	v_fmamk_f32 v132, v132, 0x3a000000, v225
	v_mul_f32_e32 v133, 0x4b800000, v132
	v_cmp_gt_f32_e32 vcc, s23, v132
	v_lshlrev_b64 v[134:135], 6, v[130:131]
	v_lshl_add_u64 v[134:135], v[192:193], 0, v[134:135]
	v_cndmask_b32_e32 v132, v132, v133, vcc
	v_rsq_f32_e32 v132, v132
	s_nop 0
	v_mul_f32_e32 v130, 0x45800000, v132
	v_cndmask_b32_e32 v136, v132, v130, vcc
	ds_read_b32 v136, v242 offset:576
	s_waitcnt lgkmcnt(0)
	v_pk_mul_f32 v[132:133], v[56:57], v[136:137] op_sel_hi:[1,0]
	v_pk_mul_f32 v[130:131], v[54:55], v[136:137] op_sel_hi:[1,0]
	global_store_dwordx4 v[134:135], v[130:133], off
	s_nop 1
	v_pk_mul_f32 v[132:133], v[52:53], v[136:137] op_sel_hi:[1,0]
	v_pk_mul_f32 v[130:131], v[50:51], v[136:137] op_sel_hi:[1,0]
	global_store_dwordx4 v[134:135], v[130:133], off offset:16
.LBB0_611:
	s_or_b64 exec, exec, s[44:45]
	s_nop 0
	v_add_u32_e32 v130, 0xa0, v162
	v_ashrrev_i32_e32 v131, 31, v130
	s_waitcnt lgkmcnt(0)
	v_lshlrev_b64 v[132:133], 7, v[130:131]
	v_lshl_add_u64 v[136:137], v[190:191], 0, v[132:133]
	s_nop 0
	s_nop 0
	s_nop 0
	s_nop 0
	v_add_f32_e32 v132, v132, v133
	v_add_f32_e32 v133, v134, v135
	s_nop 0
	v_add_f32_e32 v134, v136, v137
	v_add_f32_e32 v135, v138, v139
	v_add_f32_e32 v132, v132, v133
	v_add_f32_e32 v133, v134, v135
	v_add_f32_e32 v132, v132, v133
	s_nop 0
	s_waitcnt lgkmcnt(0)
	v_add_f32_e32 v132, v132, v133
	s_nop 0
	s_and_saveexec_b64 s[44:45], s[52:53]
	s_cbranch_execz .LBB0_613
	s_waitcnt lgkmcnt(0)
	v_add_f32_e32 v132, v132, v133
	v_fmamk_f32 v132, v132, 0x3a000000, v225
	v_mul_f32_e32 v133, 0x4b800000, v132
	v_cmp_gt_f32_e32 vcc, s23, v132
	v_lshlrev_b64 v[134:135], 6, v[130:131]
	v_lshl_add_u64 v[134:135], v[192:193], 0, v[134:135]
	v_cndmask_b32_e32 v132, v132, v133, vcc
	v_rsq_f32_e32 v132, v132
	s_nop 0
	v_mul_f32_e32 v130, 0x45800000, v132
	v_cndmask_b32_e32 v136, v132, v130, vcc
	ds_read_b32 v136, v242 offset:640
	s_waitcnt lgkmcnt(0)
	v_pk_mul_f32 v[132:133], v[40:41], v[136:137] op_sel_hi:[1,0]
	v_pk_mul_f32 v[130:131], v[38:39], v[136:137] op_sel_hi:[1,0]
	global_store_dwordx4 v[134:135], v[130:133], off
	s_nop 1
	v_pk_mul_f32 v[132:133], v[36:37], v[136:137] op_sel_hi:[1,0]
	v_pk_mul_f32 v[130:131], v[34:35], v[136:137] op_sel_hi:[1,0]
	global_store_dwordx4 v[134:135], v[130:133], off offset:16
.LBB0_613:
	s_or_b64 exec, exec, s[44:45]
	s_nop 0
	v_add_u32_e32 v130, 0xb0, v162
	v_ashrrev_i32_e32 v131, 31, v130
	s_waitcnt lgkmcnt(0)
	v_lshlrev_b64 v[132:133], 7, v[130:131]
	v_lshl_add_u64 v[136:137], v[190:191], 0, v[132:133]
	s_nop 0
	s_nop 0
	s_nop 0
	s_nop 0
	v_add_f32_e32 v132, v132, v133
	v_add_f32_e32 v133, v134, v135
	s_nop 0
	v_add_f32_e32 v134, v136, v137
	v_add_f32_e32 v135, v138, v139
	v_add_f32_e32 v132, v132, v133
	v_add_f32_e32 v133, v134, v135
	v_add_f32_e32 v132, v132, v133
	s_nop 0
	s_waitcnt lgkmcnt(0)
	v_add_f32_e32 v132, v132, v133
	s_nop 0
	s_and_saveexec_b64 s[44:45], s[52:53]
	s_cbranch_execz .LBB0_615
	s_waitcnt lgkmcnt(0)
	v_add_f32_e32 v132, v132, v133
	v_fmamk_f32 v132, v132, 0x3a000000, v225
	v_mul_f32_e32 v133, 0x4b800000, v132
	v_cmp_gt_f32_e32 vcc, s23, v132
	v_lshlrev_b64 v[134:135], 6, v[130:131]
	v_lshl_add_u64 v[134:135], v[192:193], 0, v[134:135]
	v_cndmask_b32_e32 v132, v132, v133, vcc
	v_rsq_f32_e32 v132, v132
	s_nop 0
	v_mul_f32_e32 v130, 0x45800000, v132
	v_cndmask_b32_e32 v136, v132, v130, vcc
	ds_read_b32 v136, v242 offset:704
	s_waitcnt lgkmcnt(0)
	v_pk_mul_f32 v[132:133], v[24:25], v[136:137] op_sel_hi:[1,0]
	v_pk_mul_f32 v[130:131], v[22:23], v[136:137] op_sel_hi:[1,0]
	global_store_dwordx4 v[134:135], v[130:133], off
	s_nop 1
	v_pk_mul_f32 v[132:133], v[20:21], v[136:137] op_sel_hi:[1,0]
	v_pk_mul_f32 v[130:131], v[18:19], v[136:137] op_sel_hi:[1,0]
	global_store_dwordx4 v[134:135], v[130:133], off offset:16

; __device__ __forceinline__ void row_rstd8(const float* ssp, int row0, int fq, float (&rs)[2][4]) {
; #pragma unroll
;     for (int ai = 0; ai < 2; ++ai) {
;         f32x4 a[4], b[4];
; #pragma unroll
;         for (int m = 0; m < 4; ++m) { const float* q = ssp + (size_t)(row0 + ai * HALF + m * 16) * 32 + fq * 8; a[m] = *(const f32x4*)q; b[m] = *(const f32x4*)(q + 4); }
; #pragma unroll
;         for (int m = 0; m < 4; ++m) {
;             float s = ((a[m][0] + a[m][1]) + (a[m][2] + a[m][3])) + ((b[m][0] + b[m][1]) + (b[m][2] + b[m][3]));
;             s += __shfl_xor(s, 16); s += __shfl_xor(s, 32);
;             rs[ai][m] = rsqrtf(s * (1.0f / D) + 1e-6f);
;         }
;     }
; }
;     __device__ __forceinline__ void plain(const f32x4 (&acc)[2][2][4][2], bf16_t* base, int ld, int colbase, int row0, int cl) const {
;         const int fq = (cl >> 3) & 3;
;         const float* ssin = (const float*)(ws + OFF_SUMSQ) + (size_t)ssi * SS_SLOT;
;         float rsv[2][4];
;         row_rstd8(ssin, row0, fq, rsv);
; #pragma unroll
;         for (int ai = 0; ai < 2; ++ai)
; #pragma unroll
;             for (int m = 0; m < 4; ++m) {
;                 const int row = row0 + ai * HALF + m * 16;
;                 const float rs = rsv[ai][m];
;                 bf16_t* rp = base + (size_t)row * ld + colbase + cl;
.LBB0_616:
	s_and_b64 vcc, exec, s[44:45]
	s_cbranch_vccz .LBB0_618
	v_ashrrev_i32_e32 v163, 31, v162
	s_waitcnt lgkmcnt(0)
	v_lshlrev_b64 v[130:131], 7, v[162:163]
	v_lshl_add_u64 v[134:135], v[190:191], 0, v[130:131]
	v_or_b32_e32 v168, 16, v162
	s_nop 0
	s_nop 0
	s_nop 0
	v_ashrrev_i32_e32 v169, 31, v168
	v_lshlrev_b64 v[138:139], 7, v[168:169]
	v_lshl_add_u64 v[142:143], v[190:191], 0, v[138:139]
	s_nop 0
	s_nop 0
	s_nop 0
	v_or_b32_e32 v166, 32, v162
	v_ashrrev_i32_e32 v167, 31, v166
	v_lshlrev_b64 v[146:147], 7, v[166:167]
	v_or_b32_e32 v164, 48, v162
	v_lshl_add_u64 v[150:151], v[190:191], 0, v[146:147]
	v_ashrrev_i32_e32 v165, 31, v164
	s_nop 0
	s_nop 0
	s_nop 0
	v_lshlrev_b64 v[154:155], 7, v[164:165]
	v_lshl_add_u64 v[158:159], v[190:191], 0, v[154:155]
	s_nop 0
	s_nop 0
	s_nop 0
	s_mov_b32 s30, 0x358637bd
	v_mov_b64_e32 v[202:203], s[30:31]
	v_add_u32_e32 v210, 0x80, v162
	v_ashrrev_i32_e32 v211, 31, v210
	v_add_u32_e32 v208, 0x90, v162
	v_ashrrev_i32_e32 v209, 31, v208
	v_add_u32_e32 v206, 0xa0, v162
	v_ashrrev_i32_e32 v207, 31, v206
	v_add_u32_e32 v204, 0xb0, v162
	v_ashrrev_i32_e32 v205, 31, v204
	s_lshl_b32 s56, s82, 8
	s_ashr_i32 s57, s56, 31
	s_nop 0
	v_mov_b32_e32 v174, v130
	v_mov_b32_e32 v175, v134
	v_mov_b32_e32 v134, v131
	v_pk_add_f32 v[130:131], v[174:175], v[134:135]
	v_mov_b32_e32 v134, v132
	v_mov_b32_e32 v135, v136
	v_mov_b32_e32 v136, v133
	v_pk_add_f32 v[132:133], v[134:135], v[136:137]
	v_mov_b32_e32 v134, v140
	v_pk_add_f32 v[130:131], v[130:131], v[132:133]
	v_mov_b32_e32 v132, v138
	v_mov_b32_e32 v133, v142
	v_mov_b32_e32 v142, v139
	v_mov_b32_e32 v135, v144
	v_mov_b32_e32 v144, v141
	v_pk_add_f32 v[132:133], v[132:133], v[142:143]
	v_pk_add_f32 v[134:135], v[134:135], v[144:145]
	s_nop 0
	v_pk_add_f32 v[132:133], v[132:133], v[134:135]
	v_mov_b32_e32 v135, v130
	v_mov_b32_e32 v134, v132
	v_mov_b32_e32 v130, v133
	v_pk_add_f32 v[130:131], v[134:135], v[130:131]
	s_nop 0
	s_nop 0
	v_mov_b32_e32 v134, v156
	v_mov_b32_e32 v135, v160
	v_mov_b32_e32 v160, v157
	v_pk_add_f32 v[134:135], v[134:135], v[160:161]
	s_waitcnt lgkmcnt(0)
	v_pk_add_f32 v[130:131], v[130:131], v[132:133]
	s_nop 0
	s_nop 0
	s_waitcnt lgkmcnt(0)
	v_pk_add_f32 v[130:131], v[130:131], v[132:133]
	s_nop 0
	v_pk_fma_f32 v[130:131], v[130:131], s[22:23], v[202:203] op_sel_hi:[1,0,0]
	v_mov_b32_e32 v133, v152
	v_mul_f32_e32 v132, 0x4b800000, v131
	v_cmp_gt_f32_e64 s[44:45], s23, v131
	v_cmp_gt_f32_e32 vcc, s23, v130
	v_mov_b32_e32 v152, v149
	v_cndmask_b32_e64 v131, v131, v132, s[44:45]
	v_rsq_f32_e32 v131, v131
	s_nop 0
	v_mul_f32_e32 v132, 0x45800000, v131
	v_cndmask_b32_e64 v176, v131, v132, s[44:45]
	ds_read_b32 v176, v242 offset:0
	v_mul_f32_e32 v131, 0x4b800000, v130
	v_cndmask_b32_e32 v130, v130, v131, vcc
	v_rsq_f32_e32 v130, v130
	v_mov_b32_e32 v132, v148
	v_pk_add_f32 v[132:133], v[132:133], v[152:153]
	v_mul_f32_e32 v131, 0x45800000, v130
	v_cndmask_b32_e32 v172, v130, v131, vcc
	ds_read_b32 v172, v242 offset:64
	v_mov_b32_e32 v130, v146
	v_mov_b32_e32 v131, v150
	v_mov_b32_e32 v150, v147
	v_pk_add_f32 v[130:131], v[130:131], v[150:151]
	v_lshlrev_b64 v[146:147], 7, v[204:205]
	v_pk_add_f32 v[130:131], v[130:131], v[132:133]
	v_mov_b32_e32 v132, v154
	v_mov_b32_e32 v133, v158
	v_mov_b32_e32 v158, v155
	v_pk_add_f32 v[132:133], v[132:133], v[158:159]
	v_lshl_add_u64 v[146:147], v[190:191], 0, v[146:147]
	v_pk_add_f32 v[132:133], v[132:133], v[134:135]
	v_mov_b32_e32 v135, v130
	v_mov_b32_e32 v134, v132
	v_mov_b32_e32 v130, v133
	v_pk_add_f32 v[130:131], v[134:135], v[130:131]
	s_nop 0
	s_nop 0
	s_waitcnt lgkmcnt(0)
	v_pk_add_f32 v[130:131], v[130:131], v[132:133]
	s_nop 0
	s_nop 0
	s_waitcnt lgkmcnt(0)
	v_pk_add_f32 v[130:131], v[130:131], v[132:133]
	s_nop 0
	v_pk_fma_f32 v[130:131], v[130:131], s[22:23], v[202:203] op_sel_hi:[1,0,0]
	s_nop 0
	v_mul_f32_e32 v132, 0x4b800000, v131
	v_cmp_gt_f32_e64 s[44:45], s23, v131
	v_cmp_gt_f32_e32 vcc, s23, v130
	s_nop 0
	v_cndmask_b32_e64 v131, v131, v132, s[44:45]
	v_rsq_f32_e32 v131, v131
	s_nop 0
	v_mul_f32_e32 v132, 0x45800000, v131
	v_cndmask_b32_e64 v174, v131, v132, s[44:45]
	ds_read_b32 v174, v242 offset:128
	v_mul_f32_e32 v131, 0x4b800000, v130
	v_cndmask_b32_e32 v130, v130, v131, vcc
	v_rsq_f32_e32 v130, v130
	s_nop 0
	v_mul_f32_e32 v131, 0x45800000, v130
	v_cndmask_b32_e32 v170, v130, v131, vcc
	ds_read_b32 v170, v242 offset:192
	v_lshlrev_b64 v[130:131], 7, v[210:211]
	v_lshl_add_u64 v[130:131], v[190:191], 0, v[130:131]
	s_nop 0
	s_nop 0
	v_lshlrev_b64 v[130:131], 7, v[208:209]
	v_lshl_add_u64 v[130:131], v[190:191], 0, v[130:131]
	s_nop 0
	s_nop 0
	v_lshlrev_b64 v[130:131], 7, v[206:207]
	v_lshl_add_u64 v[130:131], v[190:191], 0, v[130:131]
	s_nop 0
	s_nop 0
	s_nop 0
	s_nop 0
	s_nop 0
	s_nop 0
	s_nop 0
	s_nop 0
	v_mov_b32_e32 v212, v142
	s_nop 0
	v_mov_b32_e32 v213, v138
	v_mov_b32_e32 v138, v143
	v_mov_b32_e32 v142, v144
	v_mov_b32_e32 v143, v140
	v_mov_b32_e32 v140, v145
	v_pk_add_f32 v[138:139], v[212:213], v[138:139]
	v_pk_add_f32 v[140:141], v[142:143], v[140:141]
	s_nop 0
	v_mov_b32_e32 v142, v160
	v_pk_add_f32 v[138:139], v[138:139], v[140:141]
	v_mov_b32_e32 v140, v158
	s_nop 0
	v_mov_b32_e32 v141, v154
	v_mov_b32_e32 v154, v159
	v_mov_b32_e32 v143, v156
	v_mov_b32_e32 v156, v161
	v_pk_add_f32 v[140:141], v[140:141], v[154:155]
	v_pk_add_f32 v[142:143], v[142:143], v[156:157]
	s_waitcnt lgkmcnt(0)
; __device__ __forceinline__ unsigned cvt_pk_bf16(float lo, float hi) { const f32x2_t v = {lo, hi}; return __builtin_bit_cast(unsigned, __builtin_convertvector(v, bf16x2_t)); }
;     __device__ __forceinline__ void plain(const f32x4 (&acc)[2][2][4][2], bf16_t* base, int ld, int colbase, int row0, int cl) const {
;         const int fq = (cl >> 3) & 3;
;         const float* ssin = (const float*)(ws + OFF_SUMSQ) + (size_t)ssi * SS_SLOT;
;         float rsv[2][4];
;         row_rstd8(ssin, row0, fq, rsv);
; #pragma unroll
;         for (int ai = 0; ai < 2; ++ai)
; #pragma unroll
;             for (int m = 0; m < 4; ++m) {
;                 const int row = row0 + ai * HALF + m * 16;
;                 const float rs = rsv[ai][m];
;                 bf16_t* rp = base + (size_t)row * ld + colbase + cl;
; #pragma unroll
;                 for (int bj = 0; bj < 2; ++bj) {
;                     const f32x4 v0 = acc[ai][bj][m][0] * rs, v1 = acc[ai][bj][m][1] * rs;
;                     u32x4 w; w.x = cvt_pk_bf16(v0[0], v0[1]); w.y = cvt_pk_bf16(v0[2], v0[3]); w.z = cvt_pk_bf16(v1[0], v1[1]); w.w = cvt_pk_bf16(v1[2], v1[3]);
;                     *(u32x4*)(rp + bj * HALF) = w;
;                 }
;             }
	v_pk_mul_f32 v[144:145], v[128:129], v[176:177] op_sel_hi:[1,0]
	v_pk_add_f32 v[140:141], v[140:141], v[142:143]
	v_mov_b32_e32 v143, v138
	v_mov_b32_e32 v142, v140
	v_mov_b32_e32 v138, v141
	v_pk_add_f32 v[138:139], v[142:143], v[138:139]
	s_nop 0
	s_nop 0
	s_nop 0
	v_mov_b32_e32 v142, v134
	s_nop 0
	v_mov_b32_e32 v143, v130
	v_mov_b32_e32 v130, v135
	v_mov_b32_e32 v134, v136
	v_mov_b32_e32 v135, v132
	v_mov_b32_e32 v132, v137
	v_pk_add_f32 v[130:131], v[142:143], v[130:131]
	v_pk_add_f32 v[132:133], v[134:135], v[132:133]
	s_nop 0
	v_mov_b32_e32 v134, v152
	v_pk_add_f32 v[130:131], v[130:131], v[132:133]
	v_mov_b32_e32 v132, v150
	s_nop 0
	v_mov_b32_e32 v133, v146
	v_mov_b32_e32 v146, v151
	v_mov_b32_e32 v135, v148
	v_mov_b32_e32 v148, v153
	v_pk_add_f32 v[132:133], v[132:133], v[146:147]
	v_pk_add_f32 v[134:135], v[134:135], v[148:149]
	s_waitcnt lgkmcnt(0)
	v_pk_add_f32 v[138:139], v[138:139], v[140:141]
	v_pk_add_f32 v[132:133], v[132:133], v[134:135]
	v_mov_b32_e32 v135, v130
	v_mov_b32_e32 v134, v132
	v_mov_b32_e32 v130, v133
	s_nop 0
	s_nop 0
	v_pk_add_f32 v[130:131], v[134:135], v[130:131]
	s_nop 0
	s_nop 0
	v_lshl_add_u64 v[134:135], s[56:57], 1, v[188:189]
	s_waitcnt lgkmcnt(2)
	v_pk_add_f32 v[138:139], v[138:139], v[140:141]
	v_pk_mul_f32 v[142:143], v[126:127], v[176:177] op_sel_hi:[1,0]
	v_pk_fma_f32 v[138:139], v[138:139], s[22:23], v[202:203] op_sel_hi:[1,0,0]
	s_waitcnt lgkmcnt(0)
	v_pk_add_f32 v[130:131], v[130:131], v[132:133]
	v_mul_f32_e32 v140, 0x4b800000, v139
	v_cmp_gt_f32_e64 s[44:45], s23, v139
	s_nop 0
	s_nop 0
	v_cndmask_b32_e64 v139, v139, v140, s[44:45]
	v_rsq_f32_e32 v139, v139
	v_pk_mul_f32 v[146:147], v[124:125], v[176:177] op_sel_hi:[1,0]
	v_pk_mul_f32 v[148:149], v[122:123], v[176:177] op_sel_hi:[1,0]
	s_waitcnt lgkmcnt(0)
	v_pk_add_f32 v[130:131], v[130:131], v[132:133]
	v_mul_f32_e32 v140, 0x45800000, v139
	v_pk_fma_f32 v[130:131], v[130:131], s[22:23], v[202:203] op_sel_hi:[1,0,0]
	v_cndmask_b32_e64 v140, v139, v140, s[44:45]
	ds_read_b32 v140, v242 offset:512
	v_mul_f32_e32 v132, 0x4b800000, v131
	v_cmp_gt_f32_e64 s[44:45], s23, v131
	v_cvt_pk_bf16_f32 v142, v142, v143
	v_cvt_pk_bf16_f32 v143, v144, v145
	v_cndmask_b32_e64 v131, v131, v132, s[44:45]
	v_rsq_f32_e32 v131, v131
	v_cvt_pk_bf16_f32 v144, v148, v149
	v_cvt_pk_bf16_f32 v145, v146, v147
	v_pk_mul_f32 v[146:147], v[108:109], v[176:177] op_sel_hi:[1,0]
	v_mul_f32_e32 v132, 0x45800000, v131
	v_cndmask_b32_e64 v132, v131, v132, s[44:45]
	ds_read_b32 v132, v242 offset:640
	v_mad_i64_i32 v[136:137], s[44:45], v162, s94, v[134:135]
	global_store_dwordx4 v[136:137], v[142:145], off
	v_pk_mul_f32 v[148:149], v[106:107], v[176:177] op_sel_hi:[1,0]
	v_cmp_gt_f32_e32 vcc, s23, v138
	v_pk_mul_f32 v[144:145], v[116:117], v[176:177] op_sel_hi:[1,0]
	v_pk_mul_f32 v[142:143], v[114:115], v[176:177] op_sel_hi:[1,0]
	v_mul_f32_e32 v139, 0x4b800000, v138
	v_cvt_pk_bf16_f32 v142, v142, v143
	v_cvt_pk_bf16_f32 v143, v144, v145
	v_cvt_pk_bf16_f32 v144, v148, v149
	v_cvt_pk_bf16_f32 v145, v146, v147
	global_store_dwordx4 v[136:137], v[142:145], off offset:256
	s_waitcnt lgkmcnt(0)
	v_pk_mul_f32 v[146:147], v[112:113], v[172:173] op_sel_hi:[1,0]
	v_pk_mul_f32 v[148:149], v[110:111], v[172:173] op_sel_hi:[1,0]
	v_pk_mul_f32 v[144:145], v[120:121], v[172:173] op_sel_hi:[1,0]
	v_pk_mul_f32 v[142:143], v[118:119], v[172:173] op_sel_hi:[1,0]
	v_mad_i64_i32 v[136:137], s[44:45], v168, s94, v[134:135]
	v_cvt_pk_bf16_f32 v142, v142, v143
	v_cvt_pk_bf16_f32 v143, v144, v145
	v_cvt_pk_bf16_f32 v144, v148, v149
	v_cvt_pk_bf16_f32 v145, v146, v147
	global_store_dwordx4 v[136:137], v[142:145], off
	v_pk_mul_f32 v[146:147], v[92:93], v[172:173] op_sel_hi:[1,0]
	v_pk_mul_f32 v[148:149], v[90:91], v[172:173] op_sel_hi:[1,0]
	v_pk_mul_f32 v[144:145], v[100:101], v[172:173] op_sel_hi:[1,0]
	v_pk_mul_f32 v[142:143], v[98:99], v[172:173] op_sel_hi:[1,0]
	v_cndmask_b32_e32 v138, v138, v139, vcc
	v_cvt_pk_bf16_f32 v142, v142, v143
	v_cvt_pk_bf16_f32 v143, v144, v145
	v_cvt_pk_bf16_f32 v144, v148, v149
	v_cvt_pk_bf16_f32 v145, v146, v147
	global_store_dwordx4 v[136:137], v[142:145], off offset:256
	s_waitcnt lgkmcnt(0)
	v_pk_mul_f32 v[146:147], v[96:97], v[174:175] op_sel_hi:[1,0]
	v_pk_mul_f32 v[148:149], v[94:95], v[174:175] op_sel_hi:[1,0]
	v_pk_mul_f32 v[144:145], v[104:105], v[174:175] op_sel_hi:[1,0]
	v_pk_mul_f32 v[142:143], v[102:103], v[174:175] op_sel_hi:[1,0]
	v_mad_i64_i32 v[136:137], s[44:45], v166, s94, v[134:135]
	v_cvt_pk_bf16_f32 v142, v142, v143
	v_cvt_pk_bf16_f32 v143, v144, v145
	v_cvt_pk_bf16_f32 v144, v148, v149
	v_cvt_pk_bf16_f32 v145, v146, v147
	global_store_dwordx4 v[136:137], v[142:145], off
	v_pk_mul_f32 v[146:147], v[76:77], v[174:175] op_sel_hi:[1,0]
	v_pk_mul_f32 v[148:149], v[74:75], v[174:175] op_sel_hi:[1,0]
	v_pk_mul_f32 v[144:145], v[84:85], v[174:175] op_sel_hi:[1,0]
	v_pk_mul_f32 v[142:143], v[82:83], v[174:175] op_sel_hi:[1,0]
	v_rsq_f32_e32 v138, v138
	v_cvt_pk_bf16_f32 v142, v142, v143
	v_cvt_pk_bf16_f32 v143, v144, v145
	v_cvt_pk_bf16_f32 v144, v148, v149
	v_cvt_pk_bf16_f32 v145, v146, v147
	global_store_dwordx4 v[136:137], v[142:145], off offset:256
	s_waitcnt lgkmcnt(0)
; __device__ __forceinline__ unsigned cvt_pk_bf16(float lo, float hi) { const f32x2_t v = {lo, hi}; return __builtin_bit_cast(unsigned, __builtin_convertvector(v, bf16x2_t)); }
;     __device__ __forceinline__ void plain(const f32x4 (&acc)[2][2][4][2], bf16_t* base, int ld, int colbase, int row0, int cl) const {
;     ...
;             for (int m = 0; m < 4; ++m) {
;                 const int row = row0 + ai * HALF + m * 16;
;                 const float rs = rsv[ai][m];
;                 bf16_t* rp = base + (size_t)row * ld + colbase + cl;
; #pragma unroll
;                 for (int bj = 0; bj < 2; ++bj) {
;                     const f32x4 v0 = acc[ai][bj][m][0] * rs, v1 = acc[ai][bj][m][1] * rs;
;                     u32x4 w; w.x = cvt_pk_bf16(v0[0], v0[1]); w.y = cvt_pk_bf16(v0[2], v0[3]); w.z = cvt_pk_bf16(v1[0], v1[1]); w.w = cvt_pk_bf16(v1[2], v1[3]);
;                     *(u32x4*)(rp + bj * HALF) = w;
;                 }
;             }
	v_pk_mul_f32 v[146:147], v[80:81], v[170:171] op_sel_hi:[1,0]
	v_pk_mul_f32 v[148:149], v[78:79], v[170:171] op_sel_hi:[1,0]
	v_pk_mul_f32 v[144:145], v[88:89], v[170:171] op_sel_hi:[1,0]
	v_pk_mul_f32 v[142:143], v[86:87], v[170:171] op_sel_hi:[1,0]
	v_mad_i64_i32 v[136:137], s[44:45], v164, s94, v[134:135]
	v_cvt_pk_bf16_f32 v142, v142, v143
	v_cvt_pk_bf16_f32 v143, v144, v145
	v_cvt_pk_bf16_f32 v144, v148, v149
	v_cvt_pk_bf16_f32 v145, v146, v147
	global_store_dwordx4 v[136:137], v[142:145], off
	v_pk_mul_f32 v[146:147], v[68:69], v[170:171] op_sel_hi:[1,0]
	v_pk_mul_f32 v[148:149], v[66:67], v[170:171] op_sel_hi:[1,0]
	v_pk_mul_f32 v[144:145], v[72:73], v[170:171] op_sel_hi:[1,0]
	v_pk_mul_f32 v[142:143], v[70:71], v[170:171] op_sel_hi:[1,0]
	v_mul_f32_e32 v139, 0x45800000, v138
	v_cvt_pk_bf16_f32 v142, v142, v143
	v_cvt_pk_bf16_f32 v143, v144, v145
	v_cvt_pk_bf16_f32 v144, v148, v149
	v_cvt_pk_bf16_f32 v145, v146, v147
	global_store_dwordx4 v[136:137], v[142:145], off offset:256
	s_waitcnt lgkmcnt(0)
	v_pk_mul_f32 v[146:147], v[60:61], v[140:141] op_sel_hi:[1,0]
	v_pk_mul_f32 v[148:149], v[58:59], v[140:141] op_sel_hi:[1,0]
	v_pk_mul_f32 v[144:145], v[64:65], v[140:141] op_sel_hi:[1,0]
	v_pk_mul_f32 v[142:143], v[62:63], v[140:141] op_sel_hi:[1,0]
	v_mad_i64_i32 v[136:137], s[44:45], v210, s94, v[134:135]
	v_cvt_pk_bf16_f32 v142, v142, v143
	v_cvt_pk_bf16_f32 v143, v144, v145
	v_cvt_pk_bf16_f32 v144, v148, v149
	v_cvt_pk_bf16_f32 v145, v146, v147
	global_store_dwordx4 v[136:137], v[142:145], off
	v_pk_mul_f32 v[146:147], v[44:45], v[140:141] op_sel_hi:[1,0]
	v_pk_mul_f32 v[148:149], v[42:43], v[140:141] op_sel_hi:[1,0]
	v_pk_mul_f32 v[142:143], v[48:49], v[140:141] op_sel_hi:[1,0]
	v_pk_mul_f32 v[144:145], v[46:47], v[140:141] op_sel_hi:[1,0]
	v_cndmask_b32_e32 v138, v138, v139, vcc
	ds_read_b32 v138, v242 offset:576
	v_cvt_pk_bf16_f32 v140, v144, v145
	v_cvt_pk_bf16_f32 v141, v142, v143
	v_cvt_pk_bf16_f32 v142, v148, v149
	v_cvt_pk_bf16_f32 v143, v146, v147
	v_cmp_gt_f32_e32 vcc, s23, v130
	v_mul_f32_e32 v131, 0x4b800000, v130
	global_store_dwordx4 v[136:137], v[140:143], off offset:256
	s_waitcnt lgkmcnt(0)
	v_pk_mul_f32 v[136:137], v[56:57], v[138:139] op_sel_hi:[1,0]
	v_pk_mul_f32 v[146:147], v[52:53], v[138:139] op_sel_hi:[1,0]
	v_pk_mul_f32 v[140:141], v[54:55], v[138:139] op_sel_hi:[1,0]
	v_pk_mul_f32 v[142:143], v[50:51], v[138:139] op_sel_hi:[1,0]
	v_cndmask_b32_e32 v130, v130, v131, vcc
	v_mad_i64_i32 v[144:145], s[44:45], v208, s94, v[134:135]
	v_cvt_pk_bf16_f32 v140, v140, v141
	v_cvt_pk_bf16_f32 v141, v136, v137
	v_cvt_pk_bf16_f32 v142, v142, v143
	v_cvt_pk_bf16_f32 v143, v146, v147
	v_rsq_f32_e32 v130, v130
	global_store_dwordx4 v[144:145], v[140:143], off
	v_pk_mul_f32 v[136:137], v[30:31], v[138:139] op_sel_hi:[1,0]
	v_mul_f32_e32 v131, 0x45800000, v130
	v_pk_mul_f32 v[140:141], v[32:33], v[138:139] op_sel_hi:[1,0]
	v_pk_mul_f32 v[142:143], v[28:29], v[138:139] op_sel_hi:[1,0]
	v_pk_mul_f32 v[138:139], v[26:27], v[138:139] op_sel_hi:[1,0]
	v_cvt_pk_bf16_f32 v136, v136, v137
	v_cvt_pk_bf16_f32 v137, v140, v141
	v_cvt_pk_bf16_f32 v138, v138, v139
	v_cvt_pk_bf16_f32 v139, v142, v143
	global_store_dwordx4 v[144:145], v[136:139], off offset:256
	s_waitcnt lgkmcnt(0)
	v_pk_mul_f32 v[142:143], v[36:37], v[132:133] op_sel_hi:[1,0]
	v_pk_mul_f32 v[144:145], v[34:35], v[132:133] op_sel_hi:[1,0]
	v_pk_mul_f32 v[138:139], v[40:41], v[132:133] op_sel_hi:[1,0]
	v_pk_mul_f32 v[136:137], v[38:39], v[132:133] op_sel_hi:[1,0]
	v_mad_i64_i32 v[140:141], s[44:45], v206, s94, v[134:135]
	v_cvt_pk_bf16_f32 v136, v136, v137
	v_cvt_pk_bf16_f32 v137, v138, v139
	v_cvt_pk_bf16_f32 v138, v144, v145
	v_cvt_pk_bf16_f32 v139, v142, v143
	global_store_dwordx4 v[140:141], v[136:139], off
	v_pk_mul_f32 v[142:143], v[12:13], v[132:133] op_sel_hi:[1,0]
	v_cndmask_b32_e32 v130, v130, v131, vcc
	ds_read_b32 v130, v242 offset:704
	v_pk_mul_f32 v[138:139], v[16:17], v[132:133] op_sel_hi:[1,0]
	v_pk_mul_f32 v[136:137], v[14:15], v[132:133] op_sel_hi:[1,0]
	v_pk_mul_f32 v[132:133], v[10:11], v[132:133] op_sel_hi:[1,0]
	v_cvt_pk_bf16_f32 v136, v136, v137
	v_cvt_pk_bf16_f32 v137, v138, v139
	v_cvt_pk_bf16_f32 v138, v132, v133
	v_cvt_pk_bf16_f32 v139, v142, v143
	global_store_dwordx4 v[140:141], v[136:139], off offset:256
	s_waitcnt lgkmcnt(0)
	v_pk_mul_f32 v[132:133], v[22:23], v[130:131] op_sel_hi:[1,0]
	v_pk_mul_f32 v[140:141], v[18:19], v[130:131] op_sel_hi:[1,0]
	v_mad_i64_i32 v[136:137], s[44:45], v204, s94, v[134:135]
	v_pk_mul_f32 v[134:135], v[24:25], v[130:131] op_sel_hi:[1,0]
	v_pk_mul_f32 v[138:139], v[20:21], v[130:131] op_sel_hi:[1,0]
	v_cvt_pk_bf16_f32 v132, v132, v133
	v_cvt_pk_bf16_f32 v133, v134, v135
	v_cvt_pk_bf16_f32 v134, v140, v141
	v_cvt_pk_bf16_f32 v135, v138, v139
	global_store_dwordx4 v[136:137], v[132:135], off
	v_pk_mul_f32 v[138:139], v[4:5], v[130:131] op_sel_hi:[1,0]
	v_pk_mul_f32 v[140:141], v[2:3], v[130:131] op_sel_hi:[1,0]
	v_pk_mul_f32 v[132:133], v[8:9], v[130:131] op_sel_hi:[1,0]
	v_pk_mul_f32 v[134:135], v[6:7], v[130:131] op_sel_hi:[1,0]
	v_cvt_pk_bf16_f32 v131, v132, v133
	v_cvt_pk_bf16_f32 v130, v134, v135
	v_cvt_pk_bf16_f32 v132, v140, v141
	v_cvt_pk_bf16_f32 v133, v138, v139
	global_store_dwordx4 v[136:137], v[130:133], off offset:256
; __device__ __forceinline__ void row_rstd8(const float* ssp, int row0, int fq, float (&rs)[2][4]) {
; #pragma unroll
;     for (int ai = 0; ai < 2; ++ai) {
;         f32x4 a[4], b[4];
; #pragma unroll
;         for (int m = 0; m < 4; ++m) { const float* q = ssp + (size_t)(row0 + ai * HALF + m * 16) * 32 + fq * 8; a[m] = *(const f32x4*)q; b[m] = *(const f32x4*)(q + 4); }
; #pragma unroll
;         for (int m = 0; m < 4; ++m) {
;             float s = ((a[m][0] + a[m][1]) + (a[m][2] + a[m][3])) + ((b[m][0] + b[m][1]) + (b[m][2] + b[m][3]));
;             s += __shfl_xor(s, 16); s += __shfl_xor(s, 32);
;             rs[ai][m] = rsqrtf(s * (1.0f / D) + 1e-6f);
;         }
;     }
; }
;     template <int ACT> __device__ __forceinline__ void gated(const f32x4 (&acc)[2][2][4][2], bf16_t* base, int ld, int colbase, int row0, int cl) const {
;         const int fq = (cl >> 3) & 3;
;         const float* ssin = (const float*)(ws + OFF_SUMSQ) + (size_t)ssi * SS_SLOT;
;         float rsv[2][4];
;         row_rstd8(ssin, row0, fq, rsv);
; #pragma unroll
;         for (int ai = 0; ai < 2; ++ai)
; #pragma unroll
;             for (int m = 0; m < 4; ++m) {
;                 const int row = row0 + ai * HALF + m * 16;
;                 const float rs = rsv[ai][m];
.LBB0_618:
	s_andn2_b64 vcc, exec, s[54:55]
	s_cbranch_vccnz .LBB0_547
	v_cmp_lt_i32_e32 vcc, v232, v231
	v_ashrrev_i32_e32 v163, 31, v162
	v_or_b32_e32 v160, 16, v162
	v_cndmask_b32_e32 v130, v229, v232, vcc
	v_cmp_lt_i32_e32 vcc, v230, v231
	v_lshlrev_b32_e32 v247, 2, v130
	v_ashrrev_i32_e32 v161, 31, v160
	v_cndmask_b32_e32 v130, v229, v230, vcc
	v_lshlrev_b32_e32 v246, 2, v130
	s_waitcnt lgkmcnt(0)
	v_lshlrev_b64 v[130:131], 7, v[162:163]
	v_lshl_add_u64 v[130:131], v[190:191], 0, v[130:131]
	s_nop 0
	s_nop 0
	v_lshlrev_b64 v[130:131], 7, v[160:161]
	v_lshl_add_u64 v[130:131], v[190:191], 0, v[130:131]
	s_nop 0
	s_nop 0
	v_or_b32_e32 v168, 32, v162
	v_or_b32_e32 v146, 48, v162
	v_ashrrev_i32_e32 v169, 31, v168
	v_ashrrev_i32_e32 v147, 31, v146
	v_lshlrev_b64 v[130:131], 7, v[168:169]
	v_lshlrev_b64 v[138:139], 7, v[146:147]
	v_lshl_add_u64 v[134:135], v[190:191], 0, v[130:131]
	v_lshl_add_u64 v[142:143], v[190:191], 0, v[138:139]
	s_nop 0
	s_nop 0
	s_nop 0
	s_nop 0
	s_nop 0
	s_nop 0
	s_nop 0
	v_add_u32_e32 v208, 0x80, v162
	v_add_u32_e32 v206, 0x90, v162
	v_add_u32_e32 v204, 0xa0, v162
	v_add_u32_e32 v202, 0xb0, v162
	s_cmp_gt_i32 s82, 7
	s_mov_b64 s[44:45], -1
	v_lshlrev_b64 v[216:217], 12, v[162:163]
	v_lshlrev_b64 v[212:213], 12, v[160:161]
	v_lshlrev_b64 v[210:211], 12, v[168:169]
	v_ashrrev_i32_e32 v209, 31, v208
	v_ashrrev_i32_e32 v207, 31, v206
	v_ashrrev_i32_e32 v205, 31, v204
	v_ashrrev_i32_e32 v203, 31, v202
	v_lshlrev_b64 v[214:215], 12, v[146:147]
	s_nop 0
	v_mov_b32_e32 v171, v152
	v_mov_b32_e32 v170, v164
	v_mov_b32_e32 v152, v165
	v_mov_b32_e32 v164, v166
	v_mov_b32_e32 v165, v154
	v_mov_b32_e32 v154, v167
	v_pk_add_f32 v[152:153], v[170:171], v[152:153]
	v_pk_add_f32 v[154:155], v[164:165], v[154:155]
	s_nop 0
	v_pk_add_f32 v[152:153], v[152:153], v[154:155]
	v_mov_b32_e32 v154, v156
	v_mov_b32_e32 v155, v148
	v_mov_b32_e32 v148, v157
	v_pk_add_f32 v[148:149], v[154:155], v[148:149]
	v_mov_b32_e32 v154, v158
	v_mov_b32_e32 v155, v150
	v_mov_b32_e32 v150, v159
	v_pk_add_f32 v[150:151], v[154:155], v[150:151]
	s_nop 0
	v_pk_add_f32 v[148:149], v[148:149], v[150:151]
	s_nop 0
	v_pk_add_f32 v[218:219], v[152:153], v[148:149]
	s_cbranch_scc0 .LBB0_621
	s_nop 0
	s_nop 0
	s_mov_b32 s30, 0x358637bd
	v_mov_b64_e32 v[226:227], s[30:31]
	v_mov_b32_e32 v150, v137
	v_mov_b32_e32 v151, v133
	s_waitcnt lgkmcnt(0)
	v_pk_add_f32 v[146:147], v[218:219], v[146:147]
	s_nop 0
	s_nop 0
	v_mov_b32_e32 v152, v145
	v_mov_b32_e32 v153, v141
	v_lshlrev_b64 v[162:163], 7, v[202:203]
	v_lshl_add_u64 v[162:163], v[190:191], 0, v[162:163]
	s_waitcnt lgkmcnt(0)
	v_pk_add_f32 v[146:147], v[146:147], v[148:149]
	v_mov_b32_e32 v149, v131
	v_pk_fma_f32 v[146:147], v[146:147], s[22:23], v[226:227] op_sel_hi:[1,0,0]
	s_lshl_b32 s96, s82, 8
	v_mul_f32_e32 v148, 0x4b800000, v147
	v_cmp_gt_f32_e64 s[44:45], s23, v147
	v_cmp_gt_f32_e32 vcc, s23, v146
	v_readlane_b32 s85, v254, 63
	v_cndmask_b32_e64 v147, v147, v148, s[44:45]
	v_rsq_f32_e32 v147, v147
	s_nop 0
	v_mul_f32_e32 v148, 0x45800000, v147
	v_cndmask_b32_e64 v224, v147, v148, s[44:45]
	ds_read_b32 v224, v242 offset:0
	v_mul_f32_e32 v147, 0x4b800000, v146
	v_cndmask_b32_e32 v146, v146, v147, vcc
	v_rsq_f32_e32 v146, v146
	v_mov_b32_e32 v148, v135
	v_mul_f32_e32 v147, 0x45800000, v146
	v_cndmask_b32_e32 v220, v146, v147, vcc
	ds_read_b32 v220, v242 offset:64
	v_mov_b32_e32 v146, v134
	v_mov_b32_e32 v147, v130
	v_pk_add_f32 v[146:147], v[146:147], v[148:149]
	v_mov_b32_e32 v148, v136
	v_mov_b32_e32 v149, v132
	v_pk_add_f32 v[148:149], v[148:149], v[150:151]
	v_mov_b32_e32 v150, v143
	v_pk_add_f32 v[146:147], v[146:147], v[148:149]
	v_mov_b32_e32 v148, v142
	v_mov_b32_e32 v149, v138
	v_mov_b32_e32 v151, v139
	v_pk_add_f32 v[148:149], v[148:149], v[150:151]
	v_mov_b32_e32 v150, v144
	v_mov_b32_e32 v151, v140
	v_pk_add_f32 v[150:151], v[150:151], v[152:153]
	s_nop 0
	v_pk_add_f32 v[148:149], v[148:149], v[150:151]
	v_mov_b32_e32 v151, v146
	v_mov_b32_e32 v150, v148
	v_mov_b32_e32 v146, v149
	v_pk_add_f32 v[146:147], v[150:151], v[146:147]
	s_nop 0
	s_nop 0
	s_waitcnt lgkmcnt(0)
	v_pk_add_f32 v[146:147], v[146:147], v[148:149]
	s_nop 0
	s_nop 0
	s_waitcnt lgkmcnt(0)
	v_pk_add_f32 v[146:147], v[146:147], v[148:149]
	s_nop 0
	v_pk_fma_f32 v[146:147], v[146:147], s[22:23], v[226:227] op_sel_hi:[1,0,0]
	s_nop 0
	v_mul_f32_e32 v148, 0x4b800000, v147
	v_cmp_gt_f32_e64 s[44:45], s23, v147
	v_cmp_gt_f32_e32 vcc, s23, v146
	s_nop 0
	v_cndmask_b32_e64 v147, v147, v148, s[44:45]
	v_rsq_f32_e32 v147, v147
	s_nop 0
	v_mul_f32_e32 v148, 0x45800000, v147
	v_cndmask_b32_e64 v222, v147, v148, s[44:45]
	ds_read_b32 v222, v242 offset:128
	v_mul_f32_e32 v147, 0x4b800000, v146
	v_cndmask_b32_e32 v146, v146, v147, vcc
	v_rsq_f32_e32 v146, v146
	s_nop 0
	v_mul_f32_e32 v147, 0x45800000, v146
	v_cndmask_b32_e32 v178, v146, v147, vcc
	ds_read_b32 v178, v242 offset:192
	v_lshlrev_b64 v[146:147], 7, v[208:209]
	v_lshl_add_u64 v[146:147], v[190:191], 0, v[146:147]
	s_nop 0
	s_nop 0
	v_lshlrev_b64 v[146:147], 7, v[206:207]
	v_lshl_add_u64 v[146:147], v[190:191], 0, v[146:147]
	s_nop 0
	s_nop 0
	v_lshlrev_b64 v[146:147], 7, v[204:205]
	v_lshl_add_u64 v[146:147], v[190:191], 0, v[146:147]
	s_nop 0
	s_nop 0
	s_nop 0
	s_nop 0
	s_nop 0
	s_nop 0
	s_nop 0
	s_nop 0
	v_mov_b32_e32 v248, v170
	s_nop 0
	v_mov_b32_e32 v249, v174
	v_mov_b32_e32 v174, v171
	v_pk_add_f32 v[170:171], v[248:249], v[174:175]
	v_mov_b32_e32 v174, v172
	v_mov_b32_e32 v175, v176
	v_mov_b32_e32 v176, v173
	v_pk_add_f32 v[172:173], v[174:175], v[176:177]
	s_nop 0
	v_pk_add_f32 v[170:171], v[170:171], v[172:173]
	s_nop 0
	v_mov_b32_e32 v172, v158
	s_nop 0
	v_mov_b32_e32 v173, v154
	v_mov_b32_e32 v154, v159
	v_mov_b32_e32 v158, v160
	v_mov_b32_e32 v159, v156
	v_mov_b32_e32 v156, v161
	v_pk_add_f32 v[154:155], v[172:173], v[154:155]
	v_pk_add_f32 v[156:157], v[158:159], v[156:157]
	s_nop 0
	v_mov_b32_e32 v158, v150
	v_pk_add_f32 v[154:155], v[154:155], v[156:157]
	v_mov_b32_e32 v157, v170
	v_mov_b32_e32 v156, v154
	v_mov_b32_e32 v170, v155
	v_pk_add_f32 v[154:155], v[156:157], v[170:171]
	s_nop 0
	s_nop 0
	s_nop 0
	v_mov_b32_e32 v159, v146
	v_mov_b32_e32 v146, v151
	v_mov_b32_e32 v150, v152
	v_mov_b32_e32 v151, v148
	v_mov_b32_e32 v148, v153
	v_pk_add_f32 v[146:147], v[158:159], v[146:147]
	v_pk_add_f32 v[148:149], v[150:151], v[148:149]
	s_nop 0
	v_mov_b32_e32 v150, v168
	v_pk_add_f32 v[146:147], v[146:147], v[148:149]
	v_mov_b32_e32 v148, v166
	s_nop 0
	v_mov_b32_e32 v149, v162
	v_mov_b32_e32 v162, v167
	v_mov_b32_e32 v151, v164
	v_mov_b32_e32 v164, v169
	v_pk_add_f32 v[148:149], v[148:149], v[162:163]
	v_pk_add_f32 v[150:151], v[150:151], v[164:165]
	s_waitcnt lgkmcnt(0)
; __device__ __forceinline__ float silu_f(float x) { return x * __builtin_amdgcn_rcpf(1.0f + __expf(-x)); }
;     template <int ACT> __device__ __forceinline__ void gated(const f32x4 (&acc)[2][2][4][2], bf16_t* base, int ld, int colbase, int row0, int cl) const {
;     ...
;                 float o[8];
; #pragma unroll
;                 for (int n = 0; n < 2; ++n)
; #pragma unroll
;                     for (int j = 0; j < 4; ++j) {
;                         const float g = acc[ai][0][m][n][j] * rs, u = acc[ai][1][m][n][j] * rs;
;                         o[n * 4 + j] = (ACT ? silu_f(g) : g) * u;
;                     }
;                 *(u32x4*)(base + (size_t)row * ld + colbase + cl) = pack8(o);
;             }
	v_pk_add_f32 v[154:155], v[154:155], v[156:157]
	v_pk_add_f32 v[148:149], v[148:149], v[150:151]
	v_mov_b32_e32 v151, v146
	v_mov_b32_e32 v150, v148
	v_mov_b32_e32 v146, v149
	s_nop 0
	s_nop 0
	v_pk_add_f32 v[146:147], v[150:151], v[146:147]
	s_nop 0
	s_nop 0
	s_waitcnt lgkmcnt(0)
	v_pk_mul_f32 v[160:161], v[116:117], v[224:225] op_sel_hi:[1,0]
	s_waitcnt lgkmcnt(2)
	v_pk_add_f32 v[154:155], v[154:155], v[156:157]
	v_pk_mul_f32 v[162:163], v[106:107], v[224:225] op_sel_hi:[1,0]
	v_pk_fma_f32 v[154:155], v[154:155], s[22:23], v[226:227] op_sel_hi:[1,0,0]
	s_waitcnt lgkmcnt(0)
	v_pk_add_f32 v[146:147], v[146:147], v[148:149]
	v_mul_f32_e32 v156, 0x4b800000, v155
	v_cmp_gt_f32_e64 s[44:45], s23, v155
	s_nop 0
	s_nop 0
	v_cndmask_b32_e64 v155, v155, v156, s[44:45]
	v_rsq_f32_e32 v155, v155
	v_cmp_gt_f32_e32 vcc, s23, v154
	v_pk_mul_f32 v[164:165], v[108:109], v[224:225] op_sel_hi:[1,0]
	s_waitcnt lgkmcnt(0)
	v_pk_add_f32 v[146:147], v[146:147], v[148:149]
	v_mul_f32_e32 v156, 0x45800000, v155
	v_pk_fma_f32 v[146:147], v[146:147], s[22:23], v[226:227] op_sel_hi:[1,0,0]
	v_cndmask_b32_e64 v156, v155, v156, s[44:45]
	ds_read_b32 v156, v242 offset:512
	v_mul_f32_e32 v155, 0x4b800000, v154
	v_mul_f32_e32 v148, 0x4b800000, v147
	v_cmp_gt_f32_e64 s[44:45], s23, v147
	v_cndmask_b32_e32 v154, v154, v155, vcc
	v_rsq_f32_e32 v154, v154
	v_cndmask_b32_e64 v147, v147, v148, s[44:45]
	v_rsq_f32_e32 v147, v147
	v_mul_f32_e32 v155, 0x45800000, v154
	v_cndmask_b32_e32 v154, v154, v155, vcc
	ds_read_b32 v154, v242 offset:576
	v_mul_f32_e32 v148, 0x45800000, v147
	v_cmp_gt_f32_e32 vcc, s23, v146
	v_cndmask_b32_e64 v150, v147, v148, s[44:45]
	ds_read_b32 v150, v242 offset:640
	v_mul_f32_e32 v147, 0x4b800000, v146
	v_cndmask_b32_e32 v146, v146, v147, vcc
	v_rsq_f32_e32 v146, v146
	s_mov_b64 s[44:45], 0x2c6ff800
	v_pk_mul_f32 v[148:149], v[114:115], v[224:225] op_sel_hi:[1,0]
	v_mul_f32_e32 v147, 0x45800000, v146
	v_cndmask_b32_e32 v152, v146, v147, vcc
	ds_read_b32 v152, v242 offset:704
	v_lshl_add_u64 v[146:147], v[194:195], 0, s[96:97]
	v_lshl_add_u64 v[158:159], v[146:147], 0, s[44:45]
	v_pk_mul_f32 v[146:147], v[126:127], v[224:225] op_sel_hi:[1,0]
	s_mov_b64 s[44:45], 0
	v_pk_mul_f32 v[146:147], v[146:147], v[148:149]
	v_pk_mul_f32 v[148:149], v[128:129], v[224:225] op_sel_hi:[1,0]
	v_cvt_pk_bf16_f32 v146, v146, v147
	v_pk_mul_f32 v[148:149], v[148:149], v[160:161]
	v_pk_mul_f32 v[160:161], v[122:123], v[224:225] op_sel_hi:[1,0]
	v_cvt_pk_bf16_f32 v147, v148, v149
	v_pk_mul_f32 v[160:161], v[160:161], v[162:163]
	v_pk_mul_f32 v[162:163], v[124:125], v[224:225] op_sel_hi:[1,0]
	v_cvt_pk_bf16_f32 v148, v160, v161
	v_pk_mul_f32 v[162:163], v[162:163], v[164:165]
	v_lshl_add_u64 v[160:161], v[158:159], 0, v[216:217]
	v_cvt_pk_bf16_f32 v149, v162, v163
	global_store_dwordx4 v[160:161], v[146:149], off
	s_waitcnt lgkmcnt(0)
	v_pk_mul_f32 v[160:161], v[100:101], v[220:221] op_sel_hi:[1,0]
	v_pk_mul_f32 v[162:163], v[90:91], v[220:221] op_sel_hi:[1,0]
	v_pk_mul_f32 v[146:147], v[118:119], v[220:221] op_sel_hi:[1,0]
	v_pk_mul_f32 v[148:149], v[98:99], v[220:221] op_sel_hi:[1,0]
	v_pk_mul_f32 v[164:165], v[92:93], v[220:221] op_sel_hi:[1,0]
	v_pk_mul_f32 v[146:147], v[146:147], v[148:149]
	v_pk_mul_f32 v[148:149], v[120:121], v[220:221] op_sel_hi:[1,0]
	v_cvt_pk_bf16_f32 v146, v146, v147
	v_pk_mul_f32 v[148:149], v[148:149], v[160:161]
	v_pk_mul_f32 v[160:161], v[110:111], v[220:221] op_sel_hi:[1,0]
	v_cvt_pk_bf16_f32 v147, v148, v149
	v_pk_mul_f32 v[160:161], v[160:161], v[162:163]
	v_pk_mul_f32 v[162:163], v[112:113], v[220:221] op_sel_hi:[1,0]
	v_cvt_pk_bf16_f32 v148, v160, v161
	v_pk_mul_f32 v[162:163], v[162:163], v[164:165]
	v_lshl_add_u64 v[160:161], v[158:159], 0, v[212:213]
	v_cvt_pk_bf16_f32 v149, v162, v163
	global_store_dwordx4 v[160:161], v[146:149], off
	s_waitcnt lgkmcnt(0)
	v_pk_mul_f32 v[160:161], v[84:85], v[222:223] op_sel_hi:[1,0]
	v_pk_mul_f32 v[162:163], v[74:75], v[222:223] op_sel_hi:[1,0]
	v_pk_mul_f32 v[146:147], v[102:103], v[222:223] op_sel_hi:[1,0]
	v_pk_mul_f32 v[148:149], v[82:83], v[222:223] op_sel_hi:[1,0]
	v_pk_mul_f32 v[164:165], v[76:77], v[222:223] op_sel_hi:[1,0]
	v_pk_mul_f32 v[146:147], v[146:147], v[148:149]
	v_pk_mul_f32 v[148:149], v[104:105], v[222:223] op_sel_hi:[1,0]
	v_cvt_pk_bf16_f32 v146, v146, v147
	v_pk_mul_f32 v[148:149], v[148:149], v[160:161]
	v_pk_mul_f32 v[160:161], v[94:95], v[222:223] op_sel_hi:[1,0]
	v_cvt_pk_bf16_f32 v147, v148, v149
	v_pk_mul_f32 v[160:161], v[160:161], v[162:163]
	v_pk_mul_f32 v[162:163], v[96:97], v[222:223] op_sel_hi:[1,0]
	v_cvt_pk_bf16_f32 v148, v160, v161
	v_pk_mul_f32 v[162:163], v[162:163], v[164:165]
	v_lshl_add_u64 v[160:161], v[158:159], 0, v[210:211]
	v_cvt_pk_bf16_f32 v149, v162, v163
	global_store_dwordx4 v[160:161], v[146:149], off
	s_waitcnt lgkmcnt(0)
	v_pk_mul_f32 v[160:161], v[72:73], v[178:179] op_sel_hi:[1,0]
	v_pk_mul_f32 v[162:163], v[66:67], v[178:179] op_sel_hi:[1,0]
	v_pk_mul_f32 v[146:147], v[86:87], v[178:179] op_sel_hi:[1,0]
	v_pk_mul_f32 v[148:149], v[70:71], v[178:179] op_sel_hi:[1,0]
	v_pk_mul_f32 v[164:165], v[68:69], v[178:179] op_sel_hi:[1,0]
	v_pk_mul_f32 v[146:147], v[146:147], v[148:149]
	v_pk_mul_f32 v[148:149], v[88:89], v[178:179] op_sel_hi:[1,0]
	v_cvt_pk_bf16_f32 v146, v146, v147
	v_pk_mul_f32 v[148:149], v[148:149], v[160:161]
	v_pk_mul_f32 v[160:161], v[78:79], v[178:179] op_sel_hi:[1,0]
	v_cvt_pk_bf16_f32 v147, v148, v149
	v_pk_mul_f32 v[160:161], v[160:161], v[162:163]
	v_pk_mul_f32 v[162:163], v[80:81], v[178:179] op_sel_hi:[1,0]
	v_cvt_pk_bf16_f32 v148, v160, v161
	v_pk_mul_f32 v[162:163], v[162:163], v[164:165]
	v_lshl_add_u64 v[160:161], v[158:159], 0, v[214:215]
	v_cvt_pk_bf16_f32 v149, v162, v163
	global_store_dwordx4 v[160:161], v[146:149], off
	s_waitcnt lgkmcnt(0)
; __device__ __forceinline__ float silu_f(float x) { return x * __builtin_amdgcn_rcpf(1.0f + __expf(-x)); }
;     __device__ __forceinline__ void plain(const f32x4 (&acc)[2][2][4][2], bf16_t* base, int ld, int colbase, int row0, int cl) const {
;         const int fq = (cl >> 3) & 3;
;         const float* ssin = (const float*)(ws + OFF_SUMSQ) + (size_t)ssi * SS_SLOT;
;         float rsv[2][4];
;         row_rstd8(ssin, row0, fq, rsv);
; #pragma unroll
;         for (int ai = 0; ai < 2; ++ai)
; #pragma unroll
;             for (int m = 0; m < 4; ++m) {
;                 const int row = row0 + ai * HALF + m * 16;
;                 const float rs = rsv[ai][m];
;                 bf16_t* rp = base + (size_t)row * ld + colbase + cl;
;     template <int ACT> __device__ __forceinline__ void gated(const f32x4 (&acc)[2][2][4][2], bf16_t* base, int ld, int colbase, int row0, int cl) const {
;     ...
;                 float o[8];
; #pragma unroll
;                 for (int n = 0; n < 2; ++n)
; #pragma unroll
;                     for (int j = 0; j < 4; ++j) {
;                         const float g = acc[ai][0][m][n][j] * rs, u = acc[ai][1][m][n][j] * rs;
;                         o[n * 4 + j] = (ACT ? silu_f(g) : g) * u;
;                     }
;                 *(u32x4*)(base + (size_t)row * ld + colbase + cl) = pack8(o);
;             }
	v_pk_mul_f32 v[160:161], v[48:49], v[156:157] op_sel_hi:[1,0]
	v_pk_mul_f32 v[162:163], v[42:43], v[156:157] op_sel_hi:[1,0]
	v_pk_mul_f32 v[146:147], v[62:63], v[156:157] op_sel_hi:[1,0]
	v_pk_mul_f32 v[148:149], v[46:47], v[156:157] op_sel_hi:[1,0]
	s_nop 0
	v_pk_mul_f32 v[146:147], v[146:147], v[148:149]
	v_pk_mul_f32 v[148:149], v[64:65], v[156:157] op_sel_hi:[1,0]
	v_cvt_pk_bf16_f32 v146, v146, v147
	v_pk_mul_f32 v[148:149], v[148:149], v[160:161]
	v_pk_mul_f32 v[160:161], v[58:59], v[156:157] op_sel_hi:[1,0]
	v_cvt_pk_bf16_f32 v147, v148, v149
	v_pk_mul_f32 v[160:161], v[160:161], v[162:163]
	v_pk_mul_f32 v[162:163], v[60:61], v[156:157] op_sel_hi:[1,0]
	v_pk_mul_f32 v[156:157], v[44:45], v[156:157] op_sel_hi:[1,0]
	v_cvt_pk_bf16_f32 v148, v160, v161
	v_pk_mul_f32 v[156:157], v[162:163], v[156:157]
	s_waitcnt lgkmcnt(0)
	v_pk_mul_f32 v[160:161], v[26:27], v[154:155] op_sel_hi:[1,0]
	v_cvt_pk_bf16_f32 v149, v156, v157
	v_lshlrev_b64 v[156:157], 12, v[208:209]
	v_lshl_add_u64 v[156:157], v[158:159], 0, v[156:157]
	global_store_dwordx4 v[156:157], v[146:149], off
	v_pk_mul_f32 v[156:157], v[32:33], v[154:155] op_sel_hi:[1,0]
	s_nop 0
	v_pk_mul_f32 v[146:147], v[54:55], v[154:155] op_sel_hi:[1,0]
	v_pk_mul_f32 v[148:149], v[30:31], v[154:155] op_sel_hi:[1,0]
	s_nop 0
	v_pk_mul_f32 v[146:147], v[146:147], v[148:149]
	v_pk_mul_f32 v[148:149], v[56:57], v[154:155] op_sel_hi:[1,0]
	v_cvt_pk_bf16_f32 v146, v146, v147
	v_pk_mul_f32 v[148:149], v[148:149], v[156:157]
	v_pk_mul_f32 v[156:157], v[50:51], v[154:155] op_sel_hi:[1,0]
	v_cvt_pk_bf16_f32 v147, v148, v149
	v_pk_mul_f32 v[156:157], v[156:157], v[160:161]
	v_pk_mul_f32 v[160:161], v[52:53], v[154:155] op_sel_hi:[1,0]
	v_pk_mul_f32 v[154:155], v[28:29], v[154:155] op_sel_hi:[1,0]
	v_cvt_pk_bf16_f32 v148, v156, v157
	v_pk_mul_f32 v[154:155], v[160:161], v[154:155]
	s_waitcnt lgkmcnt(0)
	v_pk_mul_f32 v[156:157], v[10:11], v[150:151] op_sel_hi:[1,0]
	v_cvt_pk_bf16_f32 v149, v154, v155
	v_lshlrev_b64 v[154:155], 12, v[206:207]
	v_lshl_add_u64 v[154:155], v[158:159], 0, v[154:155]
	global_store_dwordx4 v[154:155], v[146:149], off
	v_pk_mul_f32 v[154:155], v[16:17], v[150:151] op_sel_hi:[1,0]
	s_nop 0
	v_pk_mul_f32 v[146:147], v[38:39], v[150:151] op_sel_hi:[1,0]
	v_pk_mul_f32 v[148:149], v[14:15], v[150:151] op_sel_hi:[1,0]
	s_nop 0
	v_pk_mul_f32 v[146:147], v[146:147], v[148:149]
	v_pk_mul_f32 v[148:149], v[40:41], v[150:151] op_sel_hi:[1,0]
	v_cvt_pk_bf16_f32 v146, v146, v147
	v_pk_mul_f32 v[148:149], v[148:149], v[154:155]
	v_pk_mul_f32 v[154:155], v[34:35], v[150:151] op_sel_hi:[1,0]
	v_cvt_pk_bf16_f32 v147, v148, v149
	v_pk_mul_f32 v[154:155], v[154:155], v[156:157]
	v_pk_mul_f32 v[156:157], v[36:37], v[150:151] op_sel_hi:[1,0]
	v_pk_mul_f32 v[150:151], v[12:13], v[150:151] op_sel_hi:[1,0]
	v_cvt_pk_bf16_f32 v148, v154, v155
	v_pk_mul_f32 v[150:151], v[156:157], v[150:151]
	s_waitcnt lgkmcnt(0)
	v_pk_mul_f32 v[154:155], v[2:3], v[152:153] op_sel_hi:[1,0]
	v_cvt_pk_bf16_f32 v149, v150, v151
	v_lshlrev_b64 v[150:151], 12, v[204:205]
	v_lshl_add_u64 v[150:151], v[158:159], 0, v[150:151]
	global_store_dwordx4 v[150:151], v[146:149], off
	v_pk_mul_f32 v[150:151], v[8:9], v[152:153] op_sel_hi:[1,0]
	s_nop 0
	v_pk_mul_f32 v[146:147], v[22:23], v[152:153] op_sel_hi:[1,0]
	v_pk_mul_f32 v[148:149], v[6:7], v[152:153] op_sel_hi:[1,0]
	s_nop 0
	v_pk_mul_f32 v[146:147], v[146:147], v[148:149]
	v_pk_mul_f32 v[148:149], v[24:25], v[152:153] op_sel_hi:[1,0]
	v_cvt_pk_bf16_f32 v146, v146, v147
	v_pk_mul_f32 v[148:149], v[148:149], v[150:151]
	v_pk_mul_f32 v[150:151], v[18:19], v[152:153] op_sel_hi:[1,0]
	v_cvt_pk_bf16_f32 v147, v148, v149
	v_pk_mul_f32 v[150:151], v[150:151], v[154:155]
	v_pk_mul_f32 v[154:155], v[20:21], v[152:153] op_sel_hi:[1,0]
	v_pk_mul_f32 v[152:153], v[4:5], v[152:153] op_sel_hi:[1,0]
	v_cvt_pk_bf16_f32 v148, v150, v151
	v_pk_mul_f32 v[152:153], v[154:155], v[152:153]
	v_lshlrev_b64 v[150:151], 12, v[202:203]
	v_cvt_pk_bf16_f32 v149, v152, v153
	v_lshl_add_u64 v[150:151], v[158:159], 0, v[150:151]
	global_store_dwordx4 v[150:151], v[146:149], off
.LBB0_621:
	s_andn2_b64 vcc, exec, s[44:45]
	s_cbranch_vccnz .LBB0_547
	s_nop 0
	s_nop 0
	s_mov_b32 s30, 0x358637bd
	v_mov_b64_e32 v[170:171], s[30:31]
	s_lshl_b32 s54, s82, 8
	s_ashr_i32 s55, s54, 31
	s_waitcnt lgkmcnt(0)
	v_pk_add_f32 v[146:147], v[218:219], v[146:147]
	s_nop 0
	s_nop 0
	s_waitcnt lgkmcnt(0)
	v_pk_add_f32 v[146:147], v[146:147], v[148:149]
	s_nop 0
	v_pk_fma_f32 v[146:147], v[146:147], s[22:23], v[170:171] op_sel_hi:[1,0,0]
	s_nop 0
	v_mul_f32_e32 v148, 0x4b800000, v147
	v_cmp_gt_f32_e64 s[44:45], s23, v147
	v_cmp_gt_f32_e32 vcc, s23, v146
	s_nop 0
	v_cndmask_b32_e64 v147, v147, v148, s[44:45]
	v_rsq_f32_e32 v147, v147
	s_nop 0
	v_mul_f32_e32 v148, 0x45800000, v147
	v_cndmask_b32_e64 v168, v147, v148, s[44:45]
	ds_read_b32 v168, v242 offset:0
	v_mul_f32_e32 v147, 0x4b800000, v146
	v_cndmask_b32_e32 v146, v146, v147, vcc
	v_rsq_f32_e32 v146, v146
	s_waitcnt lgkmcnt(0)
	v_pk_mul_f32 v[128:129], v[128:129], v[168:169] op_sel_hi:[1,0]
	v_pk_mul_f32 v[126:127], v[126:127], v[168:169] op_sel_hi:[1,0]
	v_pk_mul_f32 v[116:117], v[116:117], v[168:169] op_sel_hi:[1,0]
	v_mul_f32_e32 v147, 0x45800000, v146
	v_cndmask_b32_e32 v164, v146, v147, vcc
	ds_read_b32 v164, v242 offset:64
	v_mov_b32_e32 v146, v134
	v_mov_b32_e32 v147, v130
	v_mov_b32_e32 v130, v135
	v_mov_b32_e32 v134, v136
	v_mov_b32_e32 v135, v132
	v_mov_b32_e32 v132, v137
	v_pk_add_f32 v[130:131], v[146:147], v[130:131]
	v_pk_add_f32 v[132:133], v[134:135], v[132:133]
	v_mov_b32_e32 v134, v144
	v_pk_add_f32 v[130:131], v[130:131], v[132:133]
	v_mov_b32_e32 v132, v142
	v_mov_b32_e32 v133, v138
	v_mov_b32_e32 v138, v143
	v_mov_b32_e32 v135, v140
	v_mov_b32_e32 v140, v145
	v_pk_add_f32 v[132:133], v[132:133], v[138:139]
	v_pk_add_f32 v[134:135], v[134:135], v[140:141]
	v_lshlrev_b64 v[138:139], 7, v[202:203]
	v_pk_add_f32 v[132:133], v[132:133], v[134:135]
	v_mov_b32_e32 v135, v130
	v_mov_b32_e32 v134, v132
	v_mov_b32_e32 v130, v133
	v_pk_add_f32 v[130:131], v[134:135], v[130:131]
	s_nop 0
	s_nop 0
	v_lshl_add_u64 v[138:139], v[190:191], 0, v[138:139]
	v_pk_mul_f32 v[114:115], v[114:115], v[168:169] op_sel_hi:[1,0]
	s_waitcnt lgkmcnt(0)
; __device__ __forceinline__ unsigned cvt_pk_bf16(float lo, float hi) { const f32x2_t v = {lo, hi}; return __builtin_bit_cast(unsigned, __builtin_convertvector(v, bf16x2_t)); }
;     __device__ __forceinline__ void plain(const f32x4 (&acc)[2][2][4][2], bf16_t* base, int ld, int colbase, int row0, int cl) const {
;         const int fq = (cl >> 3) & 3;
;         const float* ssin = (const float*)(ws + OFF_SUMSQ) + (size_t)ssi * SS_SLOT;
;         float rsv[2][4];
;         row_rstd8(ssin, row0, fq, rsv);
; #pragma unroll
;         for (int ai = 0; ai < 2; ++ai)
; #pragma unroll
;             for (int m = 0; m < 4; ++m) {
;                 const int row = row0 + ai * HALF + m * 16;
;                 const float rs = rsv[ai][m];
;                 bf16_t* rp = base + (size_t)row * ld + colbase + cl;
; #pragma unroll
;                 for (int bj = 0; bj < 2; ++bj) {
;                     const f32x4 v0 = acc[ai][bj][m][0] * rs, v1 = acc[ai][bj][m][1] * rs;
;                     u32x4 w; w.x = cvt_pk_bf16(v0[0], v0[1]); w.y = cvt_pk_bf16(v0[2], v0[3]); w.z = cvt_pk_bf16(v1[0], v1[1]); w.w = cvt_pk_bf16(v1[2], v1[3]);
;                     *(u32x4*)(rp + bj * HALF) = w;
;                 }
;             }
	v_pk_mul_f32 v[112:113], v[112:113], v[164:165] op_sel_hi:[1,0]
	v_pk_mul_f32 v[110:111], v[110:111], v[164:165] op_sel_hi:[1,0]
	s_waitcnt lgkmcnt(0)
	v_pk_add_f32 v[130:131], v[130:131], v[132:133]
	s_nop 0
	s_nop 0
	v_pk_mul_f32 v[100:101], v[100:101], v[164:165] op_sel_hi:[1,0]
	v_pk_mul_f32 v[98:99], v[98:99], v[164:165] op_sel_hi:[1,0]
	s_waitcnt lgkmcnt(0)
	v_pk_add_f32 v[130:131], v[130:131], v[132:133]
	s_nop 0
	v_pk_fma_f32 v[130:131], v[130:131], s[22:23], v[170:171] op_sel_hi:[1,0,0]
	s_nop 0
	v_mul_f32_e32 v132, 0x4b800000, v131
	v_cmp_gt_f32_e64 s[44:45], s23, v131
	v_cmp_gt_f32_e32 vcc, s23, v130
	s_nop 0
	v_cndmask_b32_e64 v131, v131, v132, s[44:45]
	v_rsq_f32_e32 v131, v131
	s_nop 0
	v_mul_f32_e32 v132, 0x45800000, v131
	v_cndmask_b32_e64 v166, v131, v132, s[44:45]
	ds_read_b32 v166, v242 offset:128
	v_mul_f32_e32 v131, 0x4b800000, v130
	v_cndmask_b32_e32 v130, v130, v131, vcc
	v_rsq_f32_e32 v130, v130
	s_waitcnt lgkmcnt(0)
	v_pk_mul_f32 v[96:97], v[96:97], v[166:167] op_sel_hi:[1,0]
	v_pk_mul_f32 v[94:95], v[94:95], v[166:167] op_sel_hi:[1,0]
	v_pk_mul_f32 v[84:85], v[84:85], v[166:167] op_sel_hi:[1,0]
	v_mul_f32_e32 v131, 0x45800000, v130
	v_cndmask_b32_e32 v162, v130, v131, vcc
	ds_read_b32 v162, v242 offset:192
	v_lshlrev_b64 v[130:131], 7, v[208:209]
	v_lshl_add_u64 v[130:131], v[190:191], 0, v[130:131]
	s_nop 0
	s_nop 0
	v_lshlrev_b64 v[130:131], 7, v[206:207]
	v_lshl_add_u64 v[130:131], v[190:191], 0, v[130:131]
	s_nop 0
	s_nop 0
	v_lshlrev_b64 v[130:131], 7, v[204:205]
	v_lshl_add_u64 v[130:131], v[190:191], 0, v[130:131]
	s_nop 0
	s_nop 0
	s_nop 0
	s_nop 0
	s_nop 0
	s_nop 0
	s_nop 0
	v_pk_mul_f32 v[82:83], v[82:83], v[166:167] op_sel_hi:[1,0]
	s_waitcnt lgkmcnt(0)
	v_pk_mul_f32 v[80:81], v[80:81], v[162:163] op_sel_hi:[1,0]
	v_pk_mul_f32 v[78:79], v[78:79], v[162:163] op_sel_hi:[1,0]
	v_pk_mul_f32 v[72:73], v[72:73], v[162:163] op_sel_hi:[1,0]
	v_pk_mul_f32 v[70:71], v[70:71], v[162:163] op_sel_hi:[1,0]
	s_nop 0
	v_mov_b32_e32 v172, v154
	s_nop 0
	v_mov_b32_e32 v173, v158
	v_mov_b32_e32 v158, v155
	v_pk_add_f32 v[154:155], v[172:173], v[158:159]
	v_mov_b32_e32 v158, v156
	v_mov_b32_e32 v159, v160
	v_mov_b32_e32 v160, v157
	v_pk_add_f32 v[156:157], v[158:159], v[160:161]
	s_nop 0
	v_pk_add_f32 v[154:155], v[154:155], v[156:157]
	s_nop 0
	v_mov_b32_e32 v156, v150
	s_nop 0
	v_mov_b32_e32 v157, v146
	v_mov_b32_e32 v146, v151
	v_mov_b32_e32 v150, v152
	v_mov_b32_e32 v151, v148
	v_mov_b32_e32 v148, v153
	v_pk_add_f32 v[146:147], v[156:157], v[146:147]
	v_pk_add_f32 v[148:149], v[150:151], v[148:149]
	s_nop 0
	v_mov_b32_e32 v150, v134
	v_pk_add_f32 v[146:147], v[146:147], v[148:149]
	v_mov_b32_e32 v149, v154
	v_mov_b32_e32 v148, v146
	v_mov_b32_e32 v154, v147
	v_pk_add_f32 v[146:147], v[148:149], v[154:155]
	s_nop 0
	s_nop 0
	s_nop 0
	v_mov_b32_e32 v151, v130
	v_mov_b32_e32 v130, v135
	v_mov_b32_e32 v134, v136
	v_mov_b32_e32 v135, v132
	v_mov_b32_e32 v132, v137
	v_pk_add_f32 v[130:131], v[150:151], v[130:131]
	v_pk_add_f32 v[132:133], v[134:135], v[132:133]
	s_nop 0
	v_mov_b32_e32 v134, v144
	v_pk_add_f32 v[130:131], v[130:131], v[132:133]
	v_mov_b32_e32 v132, v142
	s_nop 0
	v_mov_b32_e32 v133, v138
	v_mov_b32_e32 v138, v143
	v_mov_b32_e32 v135, v140
	v_mov_b32_e32 v140, v145
	v_pk_add_f32 v[132:133], v[132:133], v[138:139]
	v_pk_add_f32 v[134:135], v[134:135], v[140:141]
	s_waitcnt lgkmcnt(0)
	v_pk_add_f32 v[146:147], v[146:147], v[148:149]
	v_pk_add_f32 v[132:133], v[132:133], v[134:135]
	s_nop 0
	s_nop 0
	v_mov_b32_e32 v134, v132
	v_mov_b32_e32 v135, v130
	v_mov_b32_e32 v130, v133
	v_pk_add_f32 v[130:131], v[134:135], v[130:131]
	v_lshl_add_u64 v[134:135], s[54:55], 1, v[188:189]
	v_pk_mul_f32 v[138:139], v[124:125], v[168:169] op_sel_hi:[1,0]
	v_pk_mul_f32 v[124:125], v[122:123], v[168:169] op_sel_hi:[1,0]
	v_lshl_add_u64 v[136:137], v[134:135], 0, v[216:217]
	v_cvt_pk_bf16_f32 v122, v126, v127
	v_cvt_pk_bf16_f32 v123, v128, v129
	v_cvt_pk_bf16_f32 v124, v124, v125
	v_cvt_pk_bf16_f32 v125, v138, v139
	global_store_dwordx4 v[136:137], v[122:125], off
	s_nop 0
	s_nop 0
	v_pk_mul_f32 v[122:123], v[108:109], v[168:169] op_sel_hi:[1,0]
	v_pk_mul_f32 v[108:109], v[106:107], v[168:169] op_sel_hi:[1,0]
	v_cvt_pk_bf16_f32 v106, v114, v115
	v_cvt_pk_bf16_f32 v107, v116, v117
	v_cvt_pk_bf16_f32 v108, v108, v109
	v_cvt_pk_bf16_f32 v109, v122, v123
	s_waitcnt lgkmcnt(2)
	v_pk_add_f32 v[146:147], v[146:147], v[148:149]
	global_store_dwordx4 v[136:137], v[106:109], off offset:256
	v_pk_fma_f32 v[146:147], v[146:147], s[22:23], v[170:171] op_sel_hi:[1,0,0]
	v_lshl_add_u64 v[114:115], v[134:135], 0, v[212:213]
	v_pk_mul_f32 v[108:109], v[120:121], v[164:165] op_sel_hi:[1,0]
	v_pk_mul_f32 v[106:107], v[118:119], v[164:165] op_sel_hi:[1,0]
	v_mul_f32_e32 v148, 0x4b800000, v147
	v_cvt_pk_bf16_f32 v106, v106, v107
	v_cvt_pk_bf16_f32 v107, v108, v109
	v_cvt_pk_bf16_f32 v108, v110, v111
	v_cvt_pk_bf16_f32 v109, v112, v113
	v_cmp_gt_f32_e64 s[44:45], s23, v147
	global_store_dwordx4 v[114:115], v[106:109], off
	s_waitcnt lgkmcnt(0)
; __device__ __forceinline__ unsigned cvt_pk_bf16(float lo, float hi) { const f32x2_t v = {lo, hi}; return __builtin_bit_cast(unsigned, __builtin_convertvector(v, bf16x2_t)); }
;     __device__ __forceinline__ void plain(const f32x4 (&acc)[2][2][4][2], bf16_t* base, int ld, int colbase, int row0, int cl) const {
;     ...
;             for (int m = 0; m < 4; ++m) {
;                 const int row = row0 + ai * HALF + m * 16;
;                 const float rs = rsv[ai][m];
;                 bf16_t* rp = base + (size_t)row * ld + colbase + cl;
; #pragma unroll
;                 for (int bj = 0; bj < 2; ++bj) {
;                     const f32x4 v0 = acc[ai][bj][m][0] * rs, v1 = acc[ai][bj][m][1] * rs;
;                     u32x4 w; w.x = cvt_pk_bf16(v0[0], v0[1]); w.y = cvt_pk_bf16(v0[2], v0[3]); w.z = cvt_pk_bf16(v1[0], v1[1]); w.w = cvt_pk_bf16(v1[2], v1[3]);
;                     *(u32x4*)(rp + bj * HALF) = w;
;                 }
;             }
	v_pk_add_f32 v[130:131], v[130:131], v[132:133]
	v_cndmask_b32_e64 v147, v147, v148, s[44:45]
	v_pk_mul_f32 v[106:107], v[92:93], v[164:165] op_sel_hi:[1,0]
	v_pk_mul_f32 v[92:93], v[90:91], v[164:165] op_sel_hi:[1,0]
	v_cvt_pk_bf16_f32 v90, v98, v99
	v_cvt_pk_bf16_f32 v91, v100, v101
	v_cvt_pk_bf16_f32 v92, v92, v93
	v_cvt_pk_bf16_f32 v93, v106, v107
	v_rsq_f32_e32 v147, v147
	global_store_dwordx4 v[114:115], v[90:93], off offset:256
	s_nop 0
	s_nop 0
	v_pk_mul_f32 v[92:93], v[104:105], v[166:167] op_sel_hi:[1,0]
	v_pk_mul_f32 v[90:91], v[102:103], v[166:167] op_sel_hi:[1,0]
	v_lshl_add_u64 v[98:99], v[134:135], 0, v[210:211]
	v_cvt_pk_bf16_f32 v90, v90, v91
	v_cvt_pk_bf16_f32 v91, v92, v93
	v_cvt_pk_bf16_f32 v92, v94, v95
	v_cvt_pk_bf16_f32 v93, v96, v97
	global_store_dwordx4 v[98:99], v[90:93], off
	v_mul_f32_e32 v148, 0x45800000, v147
	v_cmp_gt_f32_e32 vcc, s23, v146
	v_pk_mul_f32 v[90:91], v[76:77], v[166:167] op_sel_hi:[1,0]
	v_pk_mul_f32 v[76:77], v[74:75], v[166:167] op_sel_hi:[1,0]
	v_cvt_pk_bf16_f32 v74, v82, v83
	v_cvt_pk_bf16_f32 v75, v84, v85
	v_cvt_pk_bf16_f32 v76, v76, v77
	v_cvt_pk_bf16_f32 v77, v90, v91
	global_store_dwordx4 v[98:99], v[74:77], off offset:256
	v_cndmask_b32_e64 v148, v147, v148, s[44:45]
	ds_read_b32 v148, v242 offset:512
	v_mul_f32_e32 v147, 0x4b800000, v146
	v_pk_mul_f32 v[76:77], v[88:89], v[162:163] op_sel_hi:[1,0]
	v_pk_mul_f32 v[74:75], v[86:87], v[162:163] op_sel_hi:[1,0]
	v_lshl_add_u64 v[82:83], v[134:135], 0, v[214:215]
	v_cvt_pk_bf16_f32 v74, v74, v75
	v_cvt_pk_bf16_f32 v75, v76, v77
	v_cvt_pk_bf16_f32 v76, v78, v79
	v_cvt_pk_bf16_f32 v77, v80, v81
	v_cndmask_b32_e32 v146, v146, v147, vcc
	s_waitcnt lgkmcnt(0)
	v_pk_add_f32 v[130:131], v[130:131], v[132:133]
	global_store_dwordx4 v[82:83], v[74:77], off
	v_rsq_f32_e32 v146, v146
	v_pk_fma_f32 v[130:131], v[130:131], s[22:23], v[170:171] op_sel_hi:[1,0,0]
	v_pk_mul_f32 v[74:75], v[68:69], v[162:163] op_sel_hi:[1,0]
	v_pk_mul_f32 v[68:69], v[66:67], v[162:163] op_sel_hi:[1,0]
	v_cvt_pk_bf16_f32 v66, v70, v71
	v_cvt_pk_bf16_f32 v67, v72, v73
	v_cvt_pk_bf16_f32 v68, v68, v69
	v_cvt_pk_bf16_f32 v69, v74, v75
	v_mul_f32_e32 v132, 0x4b800000, v131
	v_cmp_gt_f32_e64 s[44:45], s23, v131
	global_store_dwordx4 v[82:83], v[66:69], off offset:256
	s_waitcnt lgkmcnt(0)
	v_pk_mul_f32 v[64:65], v[64:65], v[148:149] op_sel_hi:[1,0]
	v_pk_mul_f32 v[62:63], v[62:63], v[148:149] op_sel_hi:[1,0]
	v_lshlrev_b64 v[66:67], 12, v[208:209]
	v_pk_mul_f32 v[68:69], v[60:61], v[148:149] op_sel_hi:[1,0]
	v_pk_mul_f32 v[60:61], v[58:59], v[148:149] op_sel_hi:[1,0]
	v_cndmask_b32_e64 v131, v131, v132, s[44:45]
	v_lshl_add_u64 v[66:67], v[134:135], 0, v[66:67]
	v_cvt_pk_bf16_f32 v58, v62, v63
	v_cvt_pk_bf16_f32 v59, v64, v65
	v_cvt_pk_bf16_f32 v60, v60, v61
	v_cvt_pk_bf16_f32 v61, v68, v69
	v_rsq_f32_e32 v131, v131
	global_store_dwordx4 v[66:67], v[58:61], off
	v_pk_mul_f32 v[48:49], v[48:49], v[148:149] op_sel_hi:[1,0]
	v_pk_mul_f32 v[46:47], v[46:47], v[148:149] op_sel_hi:[1,0]
	v_pk_mul_f32 v[58:59], v[44:45], v[148:149] op_sel_hi:[1,0]
	v_pk_mul_f32 v[44:45], v[42:43], v[148:149] op_sel_hi:[1,0]
	v_mul_f32_e32 v147, 0x45800000, v146
	v_cvt_pk_bf16_f32 v42, v46, v47
	v_cvt_pk_bf16_f32 v43, v48, v49
	v_cvt_pk_bf16_f32 v44, v44, v45
	v_cvt_pk_bf16_f32 v45, v58, v59
	v_cndmask_b32_e32 v146, v146, v147, vcc
	ds_read_b32 v146, v242 offset:576
	global_store_dwordx4 v[66:67], v[42:45], off offset:256
	s_waitcnt lgkmcnt(0)
	v_pk_mul_f32 v[48:49], v[52:53], v[146:147] op_sel_hi:[1,0]
	v_pk_mul_f32 v[50:51], v[50:51], v[146:147] op_sel_hi:[1,0]
	v_lshlrev_b64 v[42:43], 12, v[206:207]
	v_lshl_add_u64 v[46:47], v[134:135], 0, v[42:43]
	v_pk_mul_f32 v[44:45], v[56:57], v[146:147] op_sel_hi:[1,0]
	v_pk_mul_f32 v[42:43], v[54:55], v[146:147] op_sel_hi:[1,0]
	v_mul_f32_e32 v132, 0x45800000, v131
	v_cvt_pk_bf16_f32 v42, v42, v43
	v_cvt_pk_bf16_f32 v43, v44, v45
	v_cvt_pk_bf16_f32 v44, v50, v51
	v_cvt_pk_bf16_f32 v45, v48, v49
	v_cmp_gt_f32_e32 vcc, s23, v130
	v_cndmask_b32_e64 v132, v131, v132, s[44:45]
	ds_read_b32 v132, v242 offset:640
	v_mul_f32_e32 v131, 0x4b800000, v130
	global_store_dwordx4 v[46:47], v[42:45], off
	v_pk_mul_f32 v[32:33], v[32:33], v[146:147] op_sel_hi:[1,0]
	v_pk_mul_f32 v[30:31], v[30:31], v[146:147] op_sel_hi:[1,0]
	v_pk_mul_f32 v[42:43], v[28:29], v[146:147] op_sel_hi:[1,0]
	v_pk_mul_f32 v[28:29], v[26:27], v[146:147] op_sel_hi:[1,0]
	v_cndmask_b32_e32 v130, v130, v131, vcc
	v_cvt_pk_bf16_f32 v26, v30, v31
	v_cvt_pk_bf16_f32 v27, v32, v33
	v_cvt_pk_bf16_f32 v28, v28, v29
	v_cvt_pk_bf16_f32 v29, v42, v43
	v_rsq_f32_e32 v130, v130
	global_store_dwordx4 v[46:47], v[26:29], off offset:256
	s_waitcnt lgkmcnt(0)
	v_pk_mul_f32 v[32:33], v[36:37], v[132:133] op_sel_hi:[1,0]
	v_pk_mul_f32 v[34:35], v[34:35], v[132:133] op_sel_hi:[1,0]
	v_lshlrev_b64 v[26:27], 12, v[204:205]
	v_lshl_add_u64 v[30:31], v[134:135], 0, v[26:27]
	v_pk_mul_f32 v[28:29], v[40:41], v[132:133] op_sel_hi:[1,0]
	v_pk_mul_f32 v[26:27], v[38:39], v[132:133] op_sel_hi:[1,0]
	v_pk_mul_f32 v[16:17], v[16:17], v[132:133] op_sel_hi:[1,0]
	v_cvt_pk_bf16_f32 v26, v26, v27
	v_cvt_pk_bf16_f32 v27, v28, v29
	v_cvt_pk_bf16_f32 v28, v34, v35
	v_cvt_pk_bf16_f32 v29, v32, v33
	global_store_dwordx4 v[30:31], v[26:29], off
	v_pk_mul_f32 v[14:15], v[14:15], v[132:133] op_sel_hi:[1,0]
	v_mul_f32_e32 v131, 0x45800000, v130
	v_pk_mul_f32 v[26:27], v[12:13], v[132:133] op_sel_hi:[1,0]
	v_pk_mul_f32 v[12:13], v[10:11], v[132:133] op_sel_hi:[1,0]
	v_cvt_pk_bf16_f32 v10, v14, v15
	v_cvt_pk_bf16_f32 v11, v16, v17
	v_cvt_pk_bf16_f32 v12, v12, v13
	v_cvt_pk_bf16_f32 v13, v26, v27
	v_cndmask_b32_e32 v130, v130, v131, vcc
	ds_read_b32 v130, v242 offset:704
	global_store_dwordx4 v[30:31], v[10:13], off offset:256
	s_waitcnt lgkmcnt(0)
	v_pk_mul_f32 v[16:17], v[20:21], v[130:131] op_sel_hi:[1,0]
	v_pk_mul_f32 v[18:19], v[18:19], v[130:131] op_sel_hi:[1,0]
	v_lshlrev_b64 v[10:11], 12, v[202:203]
	v_lshl_add_u64 v[14:15], v[134:135], 0, v[10:11]
	v_pk_mul_f32 v[12:13], v[24:25], v[130:131] op_sel_hi:[1,0]
	v_pk_mul_f32 v[10:11], v[22:23], v[130:131] op_sel_hi:[1,0]
	v_pk_mul_f32 v[8:9], v[8:9], v[130:131] op_sel_hi:[1,0]
	v_cvt_pk_bf16_f32 v10, v10, v11
	v_cvt_pk_bf16_f32 v11, v12, v13
	v_cvt_pk_bf16_f32 v12, v18, v19
	v_cvt_pk_bf16_f32 v13, v16, v17
	global_store_dwordx4 v[14:15], v[10:13], off
	v_pk_mul_f32 v[6:7], v[6:7], v[130:131] op_sel_hi:[1,0]
	s_nop 0
	v_pk_mul_f32 v[10:11], v[4:5], v[130:131] op_sel_hi:[1,0]
	v_pk_mul_f32 v[4:5], v[2:3], v[130:131] op_sel_hi:[1,0]
	v_cvt_pk_bf16_f32 v2, v6, v7
	v_cvt_pk_bf16_f32 v3, v8, v9
	v_cvt_pk_bf16_f32 v4, v4, v5
	v_cvt_pk_bf16_f32 v5, v10, v11
	global_store_dwordx4 v[14:15], v[2:5], off offset:256
	s_branch .LBB0_547
